# layer-1 weight conversion moved from P0 into layer-0 P2 start on the 128 idle-early workgroups; P0 x-rows rebalanced (waves 0-1023 weights, 1024-2047 x rows)
# speedup vs baseline: 1.0156x; 1.0047x over previous
.LBB0_24:
	v_writelane_b32 v253, s36, 42
	s_nop 1
	v_writelane_b32 v253, s37, 43
	v_writelane_b32 v253, s34, 44
	s_nop 1
	v_writelane_b32 v253, s35, 45
	s_or_b64 exec, exec, s[4:5]
	s_load_dwordx16 s[12:27], s[0:1], 0x0
	s_lshl_b32 s38, s78, 3
	s_waitcnt lgkmcnt(0)
	v_writelane_b32 v253, s12, 26
	s_nop 1
	v_writelane_b32 v253, s13, 27
	v_writelane_b32 v253, s14, 28
	v_writelane_b32 v253, s15, 29
	v_writelane_b32 v253, s16, 30
	v_writelane_b32 v253, s17, 31
	v_writelane_b32 v253, s18, 32
	v_writelane_b32 v253, s19, 33
	v_writelane_b32 v253, s20, 34
	v_writelane_b32 v253, s21, 35
	v_writelane_b32 v253, s22, 36
	v_writelane_b32 v253, s23, 37
	v_writelane_b32 v253, s24, 38
	v_writelane_b32 v253, s25, 39
	v_writelane_b32 v253, s26, 40
	v_writelane_b32 v253, s27, 41
	s_load_dwordx16 s[12:27], s[0:1], 0x40
	s_lshr_b32 s0, s8, 6
	s_lshl_b32 s1, s2, 3
	s_add_i32 s36, s0, s1
	s_waitcnt lgkmcnt(0)
	v_writelane_b32 v253, s12, 10
	s_nop 1
	v_writelane_b32 v253, s13, 11
	v_writelane_b32 v253, s14, 12
	v_writelane_b32 v253, s15, 13
	v_writelane_b32 v253, s16, 14
	v_writelane_b32 v253, s17, 15
	v_writelane_b32 v253, s18, 16
	v_writelane_b32 v253, s19, 17
	v_writelane_b32 v253, s20, 18
	v_writelane_b32 v253, s21, 19
	v_writelane_b32 v253, s22, 20
	v_writelane_b32 v253, s23, 21
	v_writelane_b32 v253, s24, 22
	v_writelane_b32 v253, s25, 23
	v_writelane_b32 v253, s26, 24
	v_writelane_b32 v253, s27, 25
	s_nop 0
	v_readlane_b32 s8, v253, 0
	v_readlane_b32 s10, v253, 2
	v_readlane_b32 s11, v253, 3
	s_add_u32 s64, s10, 0x400000
	s_addc_u32 s65, s11, 0
	s_cmpk_gt_i32 s36, 0x2fff
	v_readlane_b32 s9, v253, 1
	s_cbranch_scc1 .LBB0_178
	v_and_b32_e32 v219, 31, v227
	v_lshlrev_b32_e32 v212, 4, v219
	v_lshrrev_b32_e32 v213, 5, v227
	v_lshlrev_b32_e32 v214, 2, v219
	v_and_b32_e32 v215, 64, v214
	v_add_u32_e32 v215, v215, v214
	v_lshlrev_b32_e32 v216, 5, v213
	v_readlane_b32 s8, v253, 36
	v_readlane_b32 s9, v253, 37
	v_readlane_b32 s10, v253, 34
	v_readlane_b32 s11, v253, 35
	v_readlane_b32 s12, v253, 16
	v_readlane_b32 s13, v253, 17
	v_readlane_b32 s14, v253, 18
	v_readlane_b32 s15, v253, 19
	v_readlane_b32 s16, v253, 20
	v_readlane_b32 s17, v253, 21
	v_readlane_b32 s18, v253, 22
	v_readlane_b32 s19, v253, 23
	s_mov_b32 s66, s36
	s_movk_i32 s98, 0x17ff
	s_mov_b32 s99, s38
	s_cmpk_eq_u32 s78, 0x100
	s_cbranch_scc0 .Lwt_loop
	s_movk_i32 s98, 0xbff
	s_movk_i32 s99, 0x400
	s_cmpk_lt_u32 s66, 0x400
	s_cbranch_scc1 .Lwt_loop
	s_movk_i32 s66, 0x7fff
.Lwt_loop:
	s_cmp_gt_i32 s66, s98
	s_cbranch_scc1 .Lwt_done
	s_lshl_b32 s67, s99, 1
	s_add_i32 s67, s67, s66
	s_cmp_gt_i32 s67, s98
	s_cbranch_scc1 .Lwt_single
	s_cmpk_ge_i32 s66, 0xc00
	s_cselect_b32 s0, 1, 0
	s_mul_i32 s1, s0, 0xc00
	s_sub_i32 s1, s66, s1
	s_mul_i32 s4, s0, 0x1800000
	s_add_u32 s70, s64, s4
	s_addc_u32 s71, s65, 0
	s_lshl_b32 s69, s0, 12
	s_cmpk_lt_i32 s1, 0x300
	s_cbranch_scc1 .Lwt_in_1
	s_cmpk_lt_i32 s1, 0x400
	s_cbranch_scc1 .Lwt_out_1
	s_cmpk_lt_i32 s1, 0x800
	s_cbranch_scc1 .Lwt_up_1
	s_sub_i32 s1, s1, 0x800
	s_lshr_b32 s72, s1, 3
	s_and_b32 s73, s1, 7
	s_movk_i32 s74, 0x400
	s_mul_i32 s4, s0, 0x1000000
	s_add_u32 s76, s18, s4
	s_addc_u32 s77, s19, 0
	s_mov_b32 s4, 0x1000000
	s_lshl_b32 s5, s73, 7
	s_movk_i32 s27, 0xd00
	s_branch .Lwt_join_1

.Lwt_join_1:
	s_mul_i32 s0, s72, s74
	s_lshl_b32 s0, s0, 5
	s_lshl_b32 s1, s73, 7
	s_add_i32 s0, s0, s1
	s_lshl_b32 s0, s0, 2
	s_add_u32 s20, s76, s0
	s_addc_u32 s21, s77, 0
	s_lshl_b32 s26, s74, 2
	s_lshr_b32 s0, s27, 8
	s_lshl_b32 s0, s5, s0
	s_add_i32 s0, s0, s4
	s_lshl_b32 s1, s72, 6
	s_add_i32 s0, s0, s1
	s_add_u32 s22, s70, s0
	s_addc_u32 s23, s71, 0
	s_lshl_b32 s1, s72, 7
	s_add_u32 s24, s24, s1
	s_addc_u32 s25, s25, 0
	s_lshl_b32 s0, s26, 4
	v_mad_u32_u24 v217, v213, s0, v212
	global_load_dwordx4 v[4:7], v217, s[20:21] nt
	s_add_u32 s20, s20, s26
	s_addc_u32 s21, s21, 0
	global_load_dwordx4 v[8:11], v217, s[20:21] nt
	s_add_u32 s20, s20, s26
	s_addc_u32 s21, s21, 0
	global_load_dwordx4 v[12:15], v217, s[20:21] nt
	s_add_u32 s20, s20, s26
	s_addc_u32 s21, s21, 0
	global_load_dwordx4 v[16:19], v217, s[20:21] nt
	s_add_u32 s20, s20, s26
	s_addc_u32 s21, s21, 0
	global_load_dwordx4 v[20:23], v217, s[20:21] nt
	s_add_u32 s20, s20, s26
	s_addc_u32 s21, s21, 0
	global_load_dwordx4 v[24:27], v217, s[20:21] nt
	s_add_u32 s20, s20, s26
	s_addc_u32 s21, s21, 0
	global_load_dwordx4 v[28:31], v217, s[20:21] nt
	s_add_u32 s20, s20, s26
	s_addc_u32 s21, s21, 0
	global_load_dwordx4 v[32:35], v217, s[20:21] nt
	s_add_u32 s20, s20, s26
	s_addc_u32 s21, s21, 0
	global_load_dwordx4 v[36:39], v217, s[20:21] nt
	s_add_u32 s20, s20, s26
	s_addc_u32 s21, s21, 0
	global_load_dwordx4 v[40:43], v217, s[20:21] nt
	s_add_u32 s20, s20, s26
	s_addc_u32 s21, s21, 0
	global_load_dwordx4 v[44:47], v217, s[20:21] nt
	s_add_u32 s20, s20, s26
	s_addc_u32 s21, s21, 0
	global_load_dwordx4 v[48:51], v217, s[20:21] nt
	s_add_u32 s20, s20, s26
	s_addc_u32 s21, s21, 0
	global_load_dwordx4 v[52:55], v217, s[20:21] nt
	s_add_u32 s20, s20, s26
	s_addc_u32 s21, s21, 0
	global_load_dwordx4 v[56:59], v217, s[20:21] nt
	s_add_u32 s20, s20, s26
	s_addc_u32 s21, s21, 0
	global_load_dwordx4 v[60:63], v217, s[20:21] nt
	s_add_u32 s20, s20, s26
	s_addc_u32 s21, s21, 0
	global_load_dwordx4 v[64:67], v217, s[20:21] nt
	s_add_i32 s68, s66, s99
	s_cmpk_ge_i32 s68, 0xc00
	s_cselect_b32 s0, 1, 0
	s_mul_i32 s1, s0, 0xc00
	s_sub_i32 s1, s68, s1
	s_mul_i32 s4, s0, 0x1800000
	s_add_u32 s70, s64, s4
	s_addc_u32 s71, s65, 0
	s_lshl_b32 s69, s0, 12
	s_cmpk_lt_i32 s1, 0x300
	s_cbranch_scc1 .Lwt_in_2
	s_cmpk_lt_i32 s1, 0x400
	s_cbranch_scc1 .Lwt_out_2
	s_cmpk_lt_i32 s1, 0x800
	s_cbranch_scc1 .Lwt_up_2
	s_sub_i32 s1, s1, 0x800
	s_lshr_b32 s72, s1, 3
	s_and_b32 s73, s1, 7
	s_movk_i32 s74, 0x400
	s_mul_i32 s4, s0, 0x1000000
	s_add_u32 s76, s18, s4
	s_addc_u32 s77, s19, 0
	s_mov_b32 s4, 0x1000000
	s_lshl_b32 s5, s73, 7
	s_movk_i32 s35, 0xd00
	s_branch .Lwt_join_2

.Lwt_nomul_6:
	v_cvt_pk_bf16_f32 v196, v132, v136
	v_cvt_pk_bf16_f32 v197, v140, v144
	v_cvt_pk_bf16_f32 v198, v148, v152
	v_cvt_pk_bf16_f32 v199, v156, v160
	global_store_dwordx4 v218, v[196:199], s[42:43]
	v_cvt_pk_bf16_f32 v200, v164, v168
	v_cvt_pk_bf16_f32 v201, v172, v176
	v_cvt_pk_bf16_f32 v202, v180, v184
	v_cvt_pk_bf16_f32 v203, v188, v192
	global_store_dwordx4 v218, v[200:203], s[42:43] offset:16
	s_add_u32 s42, s42, s4
	s_addc_u32 s43, s43, 0
	v_cvt_pk_bf16_f32 v204, v133, v137
	v_cvt_pk_bf16_f32 v205, v141, v145
	v_cvt_pk_bf16_f32 v206, v149, v153
	v_cvt_pk_bf16_f32 v207, v157, v161
	global_store_dwordx4 v218, v[204:207], s[42:43]
	v_cvt_pk_bf16_f32 v208, v165, v169
	v_cvt_pk_bf16_f32 v209, v173, v177
	v_cvt_pk_bf16_f32 v210, v181, v185
	v_cvt_pk_bf16_f32 v211, v189, v193
	global_store_dwordx4 v218, v[208:211], s[42:43] offset:16
	s_add_u32 s42, s42, s4
	s_addc_u32 s43, s43, 0
	v_cvt_pk_bf16_f32 v196, v134, v138
	v_cvt_pk_bf16_f32 v197, v142, v146
	v_cvt_pk_bf16_f32 v198, v150, v154
	v_cvt_pk_bf16_f32 v199, v158, v162
	global_store_dwordx4 v218, v[196:199], s[42:43]
	v_cvt_pk_bf16_f32 v200, v166, v170
	v_cvt_pk_bf16_f32 v201, v174, v178
	v_cvt_pk_bf16_f32 v202, v182, v186
	v_cvt_pk_bf16_f32 v203, v190, v194
	global_store_dwordx4 v218, v[200:203], s[42:43] offset:16
	s_add_u32 s42, s42, s4
	s_addc_u32 s43, s43, 0
	v_cvt_pk_bf16_f32 v204, v135, v139
	v_cvt_pk_bf16_f32 v205, v143, v147
	v_cvt_pk_bf16_f32 v206, v151, v155
	v_cvt_pk_bf16_f32 v207, v159, v163
	global_store_dwordx4 v218, v[204:207], s[42:43]
	v_cvt_pk_bf16_f32 v208, v167, v171
	v_cvt_pk_bf16_f32 v209, v175, v179
	v_cvt_pk_bf16_f32 v210, v183, v187
	v_cvt_pk_bf16_f32 v211, v191, v195
	global_store_dwordx4 v218, v[208:211], s[42:43] offset:16
	s_add_i32 s66, s67, s99
	s_branch .Lwt_loop

.Lwt_nomul_8:
	v_cvt_pk_bf16_f32 v196, v4, v8
	v_cvt_pk_bf16_f32 v197, v12, v16
	v_cvt_pk_bf16_f32 v198, v20, v24
	v_cvt_pk_bf16_f32 v199, v28, v32
	global_store_dwordx4 v218, v[196:199], s[22:23]
	v_cvt_pk_bf16_f32 v200, v36, v40
	v_cvt_pk_bf16_f32 v201, v44, v48
	v_cvt_pk_bf16_f32 v202, v52, v56
	v_cvt_pk_bf16_f32 v203, v60, v64
	global_store_dwordx4 v218, v[200:203], s[22:23] offset:16
	s_add_u32 s22, s22, s4
	s_addc_u32 s23, s23, 0
	v_cvt_pk_bf16_f32 v204, v5, v9
	v_cvt_pk_bf16_f32 v205, v13, v17
	v_cvt_pk_bf16_f32 v206, v21, v25
	v_cvt_pk_bf16_f32 v207, v29, v33
	global_store_dwordx4 v218, v[204:207], s[22:23]
	v_cvt_pk_bf16_f32 v208, v37, v41
	v_cvt_pk_bf16_f32 v209, v45, v49
	v_cvt_pk_bf16_f32 v210, v53, v57
	v_cvt_pk_bf16_f32 v211, v61, v65
	global_store_dwordx4 v218, v[208:211], s[22:23] offset:16
	s_add_u32 s22, s22, s4
	s_addc_u32 s23, s23, 0
	v_cvt_pk_bf16_f32 v196, v6, v10
	v_cvt_pk_bf16_f32 v197, v14, v18
	v_cvt_pk_bf16_f32 v198, v22, v26
	v_cvt_pk_bf16_f32 v199, v30, v34
	global_store_dwordx4 v218, v[196:199], s[22:23]
	v_cvt_pk_bf16_f32 v200, v38, v42
	v_cvt_pk_bf16_f32 v201, v46, v50
	v_cvt_pk_bf16_f32 v202, v54, v58
	v_cvt_pk_bf16_f32 v203, v62, v66
	global_store_dwordx4 v218, v[200:203], s[22:23] offset:16
	s_add_u32 s22, s22, s4
	s_addc_u32 s23, s23, 0
	v_cvt_pk_bf16_f32 v204, v7, v11
	v_cvt_pk_bf16_f32 v205, v15, v19
	v_cvt_pk_bf16_f32 v206, v23, v27
	v_cvt_pk_bf16_f32 v207, v31, v35
	global_store_dwordx4 v218, v[204:207], s[22:23]
	v_cvt_pk_bf16_f32 v208, v39, v43
	v_cvt_pk_bf16_f32 v209, v47, v51
	v_cvt_pk_bf16_f32 v210, v55, v59
	v_cvt_pk_bf16_f32 v211, v63, v67
	global_store_dwordx4 v218, v[208:211], s[22:23] offset:16
	s_add_i32 s66, s66, s99
	s_branch .Lwt_loop
.Lwt_done:
.LBB0_178:
	v_readlane_b32 s8, v253, 0
	v_readlane_b32 s10, v253, 2
	v_readlane_b32 s11, v253, 3
	s_add_u32 s46, s10, 0x3400000
	s_addc_u32 s47, s11, 0
	s_cmpk_lt_i32 s36, 0x4200
	s_cselect_b64 s[0:1], -1, 0
	v_readlane_b32 s9, v253, 1
	v_writelane_b32 v253, s0, 46
	s_cmpk_gt_i32 s36, 0x41ff
	v_mbcnt_lo_u32_b32 v42, -1, 0
	v_writelane_b32 v253, s1, 47
	s_cbranch_scc1 .LBB0_192
	v_mbcnt_hi_u32_b32 v3, -1, v42
	s_ashr_i32 s39, s38, 31
	v_lshlrev_b32_e32 v4, 4, v227
	v_lshlrev_b32_e32 v5, 3, v227
	v_mov_b32_e32 v12, 0
	v_xor_b32_e32 v6, 1, v227
	v_lshlrev_b32_e32 v6, 2, v6
	v_xor_b32_e32 v7, 2, v227
	v_lshlrev_b32_e32 v7, 2, v7
	v_xor_b32_e32 v8, 4, v227
	v_lshlrev_b32_e32 v8, 2, v8
	v_xor_b32_e32 v9, 8, v227
	v_lshlrev_b32_e32 v9, 2, v9
	v_xor_b32_e32 v10, 16, v227
	v_lshlrev_b32_e32 v10, 2, v10
	v_xor_b32_e32 v11, 32, v227
	v_lshlrev_b32_e32 v11, 2, v11
	v_readlane_b32 s48, v253, 26
	v_readlane_b32 s49, v253, 27
	v_readlane_b32 s50, v253, 28
	v_readlane_b32 s51, v253, 29
	v_readlane_b32 s52, v253, 44
	v_readlane_b32 s53, v253, 45
	s_mov_b32 s14, s36
	s_movk_i32 s98, 0x4200
	s_mov_b32 s99, s38
	s_cmpk_eq_u32 s78, 0x100
	s_cbranch_scc0 .Lxn_loop
	s_movk_i32 s99, 0x400
	s_cmpk_lt_u32 s36, 0x400
	s_cbranch_scc1 .Lxn_low
	s_add_i32 s14, s36, 0xfffffc00
	s_movk_i32 s98, 0x4000
	s_branch .Lxn_loop
.Lxn_low:
	s_add_i32 s14, s36, 0x4000
.Lxn_loop:
	s_cmp_lt_i32 s14, s98
	s_cbranch_scc0 .Lxn_done
	s_mul_i32 s15, s99, 7
	s_add_i32 s15, s15, s14
	s_cmp_lt_i32 s15, s98
	s_cbranch_scc0 .Lxn_try4
	s_mov_b32 s58, s14
	s_add_i32 s60, s58, 0xffffc000
	s_cmpk_lt_i32 s58, 0x4000
	s_cselect_b32 s54, s48, s50
	s_cselect_b32 s55, s49, s51
	s_cselect_b32 s59, s58, s60
	s_lshl_b32 s59, s59, 12
	s_add_u32 s54, s54, s59
	s_addc_u32 s55, s55, 0
	global_load_dwordx4 v[64:67], v4, s[54:55] nt
	global_load_dwordx4 v[68:71], v4, s[54:55] offset:1024 nt
	global_load_dwordx4 v[72:75], v4, s[54:55] offset:2048 nt
	global_load_dwordx4 v[76:79], v4, s[54:55] offset:3072 nt
	s_add_i32 s58, s58, s99
	s_add_i32 s60, s58, 0xffffc000
	s_cmpk_lt_i32 s58, 0x4000
	s_cselect_b32 s54, s48, s50
	s_cselect_b32 s55, s49, s51
	s_cselect_b32 s59, s58, s60
	s_lshl_b32 s59, s59, 12
	s_add_u32 s54, s54, s59
	s_addc_u32 s55, s55, 0
	global_load_dwordx4 v[80:83], v4, s[54:55] nt
	global_load_dwordx4 v[84:87], v4, s[54:55] offset:1024 nt
	global_load_dwordx4 v[88:91], v4, s[54:55] offset:2048 nt
	global_load_dwordx4 v[92:95], v4, s[54:55] offset:3072 nt
	s_add_i32 s58, s58, s99
	s_add_i32 s60, s58, 0xffffc000
	s_cmpk_lt_i32 s58, 0x4000
	s_cselect_b32 s54, s48, s50
	s_cselect_b32 s55, s49, s51
	s_cselect_b32 s59, s58, s60
	s_lshl_b32 s59, s59, 12
	s_add_u32 s54, s54, s59
	s_addc_u32 s55, s55, 0
	global_load_dwordx4 v[96:99], v4, s[54:55] nt
	global_load_dwordx4 v[100:103], v4, s[54:55] offset:1024 nt
	global_load_dwordx4 v[104:107], v4, s[54:55] offset:2048 nt
	global_load_dwordx4 v[108:111], v4, s[54:55] offset:3072 nt
	s_add_i32 s58, s58, s99
	s_add_i32 s60, s58, 0xffffc000
	s_cmpk_lt_i32 s58, 0x4000
	s_cselect_b32 s54, s48, s50
	s_cselect_b32 s55, s49, s51
	s_cselect_b32 s59, s58, s60
	s_lshl_b32 s59, s59, 12
	s_add_u32 s54, s54, s59
	s_addc_u32 s55, s55, 0
	global_load_dwordx4 v[112:115], v4, s[54:55] nt
	global_load_dwordx4 v[116:119], v4, s[54:55] offset:1024 nt
	global_load_dwordx4 v[120:123], v4, s[54:55] offset:2048 nt
	global_load_dwordx4 v[124:127], v4, s[54:55] offset:3072 nt
	s_add_i32 s58, s58, s99
	s_add_i32 s60, s58, 0xffffc000
	s_cmpk_lt_i32 s58, 0x4000
	s_cselect_b32 s54, s48, s50
	s_cselect_b32 s55, s49, s51
	s_cselect_b32 s59, s58, s60
	s_lshl_b32 s59, s59, 12
	s_add_u32 s54, s54, s59
	s_addc_u32 s55, s55, 0
	global_load_dwordx4 v[128:131], v4, s[54:55] nt
	global_load_dwordx4 v[132:135], v4, s[54:55] offset:1024 nt
	global_load_dwordx4 v[136:139], v4, s[54:55] offset:2048 nt
	global_load_dwordx4 v[140:143], v4, s[54:55] offset:3072 nt
	s_add_i32 s58, s58, s99
	s_add_i32 s60, s58, 0xffffc000
	s_cmpk_lt_i32 s58, 0x4000
	s_cselect_b32 s54, s48, s50
	s_cselect_b32 s55, s49, s51
	s_cselect_b32 s59, s58, s60
	s_lshl_b32 s59, s59, 12
	s_add_u32 s54, s54, s59
	s_addc_u32 s55, s55, 0
	global_load_dwordx4 v[144:147], v4, s[54:55] nt
	global_load_dwordx4 v[148:151], v4, s[54:55] offset:1024 nt
	global_load_dwordx4 v[152:155], v4, s[54:55] offset:2048 nt
	global_load_dwordx4 v[156:159], v4, s[54:55] offset:3072 nt
	s_add_i32 s58, s58, s99
	s_add_i32 s60, s58, 0xffffc000
	s_cmpk_lt_i32 s58, 0x4000
	s_cselect_b32 s54, s48, s50
	s_cselect_b32 s55, s49, s51
	s_cselect_b32 s59, s58, s60
	s_lshl_b32 s59, s59, 12
	s_add_u32 s54, s54, s59
	s_addc_u32 s55, s55, 0
	global_load_dwordx4 v[160:163], v4, s[54:55] nt
	global_load_dwordx4 v[164:167], v4, s[54:55] offset:1024 nt
	global_load_dwordx4 v[168:171], v4, s[54:55] offset:2048 nt
	global_load_dwordx4 v[172:175], v4, s[54:55] offset:3072 nt
	s_add_i32 s58, s58, s99
	s_add_i32 s60, s58, 0xffffc000
	s_cmpk_lt_i32 s58, 0x4000
	s_cselect_b32 s54, s48, s50
	s_cselect_b32 s55, s49, s51
	s_cselect_b32 s59, s58, s60
	s_lshl_b32 s59, s59, 12
	s_add_u32 s54, s54, s59
	s_addc_u32 s55, s55, 0
	global_load_dwordx4 v[176:179], v4, s[54:55] nt
	global_load_dwordx4 v[180:183], v4, s[54:55] offset:1024 nt
	global_load_dwordx4 v[184:187], v4, s[54:55] offset:2048 nt
	global_load_dwordx4 v[188:191], v4, s[54:55] offset:3072 nt
	s_mov_b32 s58, s14
	s_lshl_b32 s59, s58, 11
	s_add_u32 s56, s46, s59
	s_addc_u32 s57, s47, 0
	s_waitcnt vmcnt(28)
	v_pk_mul_f32 v[192:193], v[64:65], v[64:65]
	v_pk_fma_f32 v[192:193], v[66:67], v[66:67], v[192:193]
	v_pk_fma_f32 v[192:193], v[68:69], v[68:69], v[192:193]
	v_pk_fma_f32 v[192:193], v[70:71], v[70:71], v[192:193]
	v_pk_fma_f32 v[192:193], v[72:73], v[72:73], v[192:193]
	v_pk_fma_f32 v[192:193], v[74:75], v[74:75], v[192:193]
	v_pk_fma_f32 v[192:193], v[76:77], v[76:77], v[192:193]
	v_pk_fma_f32 v[192:193], v[78:79], v[78:79], v[192:193]
	v_cvt_pk_bf16_f32 v64, v64, v65
	v_cvt_pk_bf16_f32 v65, v66, v67
	global_store_dwordx2 v5, v[64:65], s[56:57]
	v_cvt_pk_bf16_f32 v68, v68, v69
	v_cvt_pk_bf16_f32 v69, v70, v71
	global_store_dwordx2 v5, v[68:69], s[56:57] offset:512
	v_cvt_pk_bf16_f32 v72, v72, v73
	v_cvt_pk_bf16_f32 v73, v74, v75
	global_store_dwordx2 v5, v[72:73], s[56:57] offset:1024
	v_cvt_pk_bf16_f32 v76, v76, v77
	v_cvt_pk_bf16_f32 v77, v78, v79
	global_store_dwordx2 v5, v[76:77], s[56:57] offset:1536
	v_add_f32_e32 v192, v192, v193
	s_add_i32 s58, s58, s99
	s_lshl_b32 s59, s58, 11
	s_add_u32 s56, s46, s59
	s_addc_u32 s57, s47, 0
	s_waitcnt vmcnt(28)
	v_pk_mul_f32 v[194:195], v[80:81], v[80:81]
	v_pk_fma_f32 v[194:195], v[82:83], v[82:83], v[194:195]
	v_pk_fma_f32 v[194:195], v[84:85], v[84:85], v[194:195]
	v_pk_fma_f32 v[194:195], v[86:87], v[86:87], v[194:195]
	v_pk_fma_f32 v[194:195], v[88:89], v[88:89], v[194:195]
	v_pk_fma_f32 v[194:195], v[90:91], v[90:91], v[194:195]
	v_pk_fma_f32 v[194:195], v[92:93], v[92:93], v[194:195]
	v_pk_fma_f32 v[194:195], v[94:95], v[94:95], v[194:195]
	v_cvt_pk_bf16_f32 v80, v80, v81
	v_cvt_pk_bf16_f32 v81, v82, v83
	global_store_dwordx2 v5, v[80:81], s[56:57]
	v_cvt_pk_bf16_f32 v84, v84, v85
	v_cvt_pk_bf16_f32 v85, v86, v87
	global_store_dwordx2 v5, v[84:85], s[56:57] offset:512
	v_cvt_pk_bf16_f32 v88, v88, v89
	v_cvt_pk_bf16_f32 v89, v90, v91
	global_store_dwordx2 v5, v[88:89], s[56:57] offset:1024
	v_cvt_pk_bf16_f32 v92, v92, v93
	v_cvt_pk_bf16_f32 v93, v94, v95
	global_store_dwordx2 v5, v[92:93], s[56:57] offset:1536
	v_add_f32_e32 v194, v194, v195
	s_add_i32 s58, s58, s99
	s_lshl_b32 s59, s58, 11
	s_add_u32 s56, s46, s59
	s_addc_u32 s57, s47, 0
	s_waitcnt vmcnt(28)
	v_pk_mul_f32 v[196:197], v[96:97], v[96:97]
	v_pk_fma_f32 v[196:197], v[98:99], v[98:99], v[196:197]
	v_pk_fma_f32 v[196:197], v[100:101], v[100:101], v[196:197]
	v_pk_fma_f32 v[196:197], v[102:103], v[102:103], v[196:197]
	v_pk_fma_f32 v[196:197], v[104:105], v[104:105], v[196:197]
	v_pk_fma_f32 v[196:197], v[106:107], v[106:107], v[196:197]
	v_pk_fma_f32 v[196:197], v[108:109], v[108:109], v[196:197]
	v_pk_fma_f32 v[196:197], v[110:111], v[110:111], v[196:197]
	v_cvt_pk_bf16_f32 v96, v96, v97
	v_cvt_pk_bf16_f32 v97, v98, v99
	global_store_dwordx2 v5, v[96:97], s[56:57]
	v_cvt_pk_bf16_f32 v100, v100, v101
	v_cvt_pk_bf16_f32 v101, v102, v103
	global_store_dwordx2 v5, v[100:101], s[56:57] offset:512
	v_cvt_pk_bf16_f32 v104, v104, v105
	v_cvt_pk_bf16_f32 v105, v106, v107
	global_store_dwordx2 v5, v[104:105], s[56:57] offset:1024
	v_cvt_pk_bf16_f32 v108, v108, v109
	v_cvt_pk_bf16_f32 v109, v110, v111
	global_store_dwordx2 v5, v[108:109], s[56:57] offset:1536
	v_add_f32_e32 v196, v196, v197
	s_add_i32 s58, s58, s99
	s_lshl_b32 s59, s58, 11
	s_add_u32 s56, s46, s59
	s_addc_u32 s57, s47, 0
	s_waitcnt vmcnt(28)
	v_pk_mul_f32 v[198:199], v[112:113], v[112:113]
	v_pk_fma_f32 v[198:199], v[114:115], v[114:115], v[198:199]
	v_pk_fma_f32 v[198:199], v[116:117], v[116:117], v[198:199]
	v_pk_fma_f32 v[198:199], v[118:119], v[118:119], v[198:199]
	v_pk_fma_f32 v[198:199], v[120:121], v[120:121], v[198:199]
	v_pk_fma_f32 v[198:199], v[122:123], v[122:123], v[198:199]
	v_pk_fma_f32 v[198:199], v[124:125], v[124:125], v[198:199]
	v_pk_fma_f32 v[198:199], v[126:127], v[126:127], v[198:199]
	v_cvt_pk_bf16_f32 v112, v112, v113
	v_cvt_pk_bf16_f32 v113, v114, v115
	global_store_dwordx2 v5, v[112:113], s[56:57]
	v_cvt_pk_bf16_f32 v116, v116, v117
	v_cvt_pk_bf16_f32 v117, v118, v119
	global_store_dwordx2 v5, v[116:117], s[56:57] offset:512
	v_cvt_pk_bf16_f32 v120, v120, v121
	v_cvt_pk_bf16_f32 v121, v122, v123
	global_store_dwordx2 v5, v[120:121], s[56:57] offset:1024
	v_cvt_pk_bf16_f32 v124, v124, v125
	v_cvt_pk_bf16_f32 v125, v126, v127
	global_store_dwordx2 v5, v[124:125], s[56:57] offset:1536
	v_add_f32_e32 v198, v198, v199
	s_add_i32 s58, s58, s99
	s_lshl_b32 s59, s58, 11
	s_add_u32 s56, s46, s59
	s_addc_u32 s57, s47, 0
	s_waitcnt vmcnt(28)
	v_pk_mul_f32 v[200:201], v[128:129], v[128:129]
	v_pk_fma_f32 v[200:201], v[130:131], v[130:131], v[200:201]
	v_pk_fma_f32 v[200:201], v[132:133], v[132:133], v[200:201]
	v_pk_fma_f32 v[200:201], v[134:135], v[134:135], v[200:201]
	v_pk_fma_f32 v[200:201], v[136:137], v[136:137], v[200:201]
	v_pk_fma_f32 v[200:201], v[138:139], v[138:139], v[200:201]
	v_pk_fma_f32 v[200:201], v[140:141], v[140:141], v[200:201]
	v_pk_fma_f32 v[200:201], v[142:143], v[142:143], v[200:201]
	v_cvt_pk_bf16_f32 v128, v128, v129
	v_cvt_pk_bf16_f32 v129, v130, v131
	global_store_dwordx2 v5, v[128:129], s[56:57]
	v_cvt_pk_bf16_f32 v132, v132, v133
	v_cvt_pk_bf16_f32 v133, v134, v135
	global_store_dwordx2 v5, v[132:133], s[56:57] offset:512
	v_cvt_pk_bf16_f32 v136, v136, v137
	v_cvt_pk_bf16_f32 v137, v138, v139
	global_store_dwordx2 v5, v[136:137], s[56:57] offset:1024
	v_cvt_pk_bf16_f32 v140, v140, v141
	v_cvt_pk_bf16_f32 v141, v142, v143
	global_store_dwordx2 v5, v[140:141], s[56:57] offset:1536
	v_add_f32_e32 v200, v200, v201
	s_add_i32 s58, s58, s99
	s_lshl_b32 s59, s58, 11
	s_add_u32 s56, s46, s59
	s_addc_u32 s57, s47, 0
	s_waitcnt vmcnt(28)
	v_pk_mul_f32 v[202:203], v[144:145], v[144:145]
	v_pk_fma_f32 v[202:203], v[146:147], v[146:147], v[202:203]
	v_pk_fma_f32 v[202:203], v[148:149], v[148:149], v[202:203]
	v_pk_fma_f32 v[202:203], v[150:151], v[150:151], v[202:203]
	v_pk_fma_f32 v[202:203], v[152:153], v[152:153], v[202:203]
	v_pk_fma_f32 v[202:203], v[154:155], v[154:155], v[202:203]
	v_pk_fma_f32 v[202:203], v[156:157], v[156:157], v[202:203]
	v_pk_fma_f32 v[202:203], v[158:159], v[158:159], v[202:203]
	v_cvt_pk_bf16_f32 v144, v144, v145
	v_cvt_pk_bf16_f32 v145, v146, v147
	global_store_dwordx2 v5, v[144:145], s[56:57]
	v_cvt_pk_bf16_f32 v148, v148, v149
	v_cvt_pk_bf16_f32 v149, v150, v151
	global_store_dwordx2 v5, v[148:149], s[56:57] offset:512
	v_cvt_pk_bf16_f32 v152, v152, v153
	v_cvt_pk_bf16_f32 v153, v154, v155
	global_store_dwordx2 v5, v[152:153], s[56:57] offset:1024
	v_cvt_pk_bf16_f32 v156, v156, v157
	v_cvt_pk_bf16_f32 v157, v158, v159
	global_store_dwordx2 v5, v[156:157], s[56:57] offset:1536
	v_add_f32_e32 v202, v202, v203
	s_add_i32 s58, s58, s99
	s_lshl_b32 s59, s58, 11
	s_add_u32 s56, s46, s59
	s_addc_u32 s57, s47, 0
	s_waitcnt vmcnt(28)
	v_pk_mul_f32 v[204:205], v[160:161], v[160:161]
	v_pk_fma_f32 v[204:205], v[162:163], v[162:163], v[204:205]
	v_pk_fma_f32 v[204:205], v[164:165], v[164:165], v[204:205]
	v_pk_fma_f32 v[204:205], v[166:167], v[166:167], v[204:205]
	v_pk_fma_f32 v[204:205], v[168:169], v[168:169], v[204:205]
	v_pk_fma_f32 v[204:205], v[170:171], v[170:171], v[204:205]
	v_pk_fma_f32 v[204:205], v[172:173], v[172:173], v[204:205]
	v_pk_fma_f32 v[204:205], v[174:175], v[174:175], v[204:205]
	v_cvt_pk_bf16_f32 v160, v160, v161
	v_cvt_pk_bf16_f32 v161, v162, v163
	global_store_dwordx2 v5, v[160:161], s[56:57]
	v_cvt_pk_bf16_f32 v164, v164, v165
	v_cvt_pk_bf16_f32 v165, v166, v167
	global_store_dwordx2 v5, v[164:165], s[56:57] offset:512
	v_cvt_pk_bf16_f32 v168, v168, v169
	v_cvt_pk_bf16_f32 v169, v170, v171
	global_store_dwordx2 v5, v[168:169], s[56:57] offset:1024
	v_cvt_pk_bf16_f32 v172, v172, v173
	v_cvt_pk_bf16_f32 v173, v174, v175
	global_store_dwordx2 v5, v[172:173], s[56:57] offset:1536
	v_add_f32_e32 v204, v204, v205
	s_add_i32 s58, s58, s99
	s_lshl_b32 s59, s58, 11
	s_add_u32 s56, s46, s59
	s_addc_u32 s57, s47, 0
	s_waitcnt vmcnt(28)
	v_pk_mul_f32 v[206:207], v[176:177], v[176:177]
	v_pk_fma_f32 v[206:207], v[178:179], v[178:179], v[206:207]
	v_pk_fma_f32 v[206:207], v[180:181], v[180:181], v[206:207]
	v_pk_fma_f32 v[206:207], v[182:183], v[182:183], v[206:207]
	v_pk_fma_f32 v[206:207], v[184:185], v[184:185], v[206:207]
	v_pk_fma_f32 v[206:207], v[186:187], v[186:187], v[206:207]
	v_pk_fma_f32 v[206:207], v[188:189], v[188:189], v[206:207]
	v_pk_fma_f32 v[206:207], v[190:191], v[190:191], v[206:207]
	v_cvt_pk_bf16_f32 v176, v176, v177
	v_cvt_pk_bf16_f32 v177, v178, v179
	global_store_dwordx2 v5, v[176:177], s[56:57]
	v_cvt_pk_bf16_f32 v180, v180, v181
	v_cvt_pk_bf16_f32 v181, v182, v183
	global_store_dwordx2 v5, v[180:181], s[56:57] offset:512
	v_cvt_pk_bf16_f32 v184, v184, v185
	v_cvt_pk_bf16_f32 v185, v186, v187
	global_store_dwordx2 v5, v[184:185], s[56:57] offset:1024
	v_cvt_pk_bf16_f32 v188, v188, v189
	v_cvt_pk_bf16_f32 v189, v190, v191
	global_store_dwordx2 v5, v[188:189], s[56:57] offset:1536
	v_add_f32_e32 v206, v206, v207
	ds_bpermute_b32 v193, v6, v192
	ds_bpermute_b32 v195, v6, v194
	ds_bpermute_b32 v197, v6, v196
	ds_bpermute_b32 v199, v6, v198
	ds_bpermute_b32 v201, v6, v200
	ds_bpermute_b32 v203, v6, v202
	ds_bpermute_b32 v205, v6, v204
	ds_bpermute_b32 v207, v6, v206
	s_waitcnt lgkmcnt(0)
	v_add_f32_e32 v192, v192, v193
	v_add_f32_e32 v194, v194, v195
	v_add_f32_e32 v196, v196, v197
	v_add_f32_e32 v198, v198, v199
	v_add_f32_e32 v200, v200, v201
	v_add_f32_e32 v202, v202, v203
	v_add_f32_e32 v204, v204, v205
	v_add_f32_e32 v206, v206, v207
	ds_bpermute_b32 v193, v7, v192
	ds_bpermute_b32 v195, v7, v194
	ds_bpermute_b32 v197, v7, v196
	ds_bpermute_b32 v199, v7, v198
	ds_bpermute_b32 v201, v7, v200
	ds_bpermute_b32 v203, v7, v202
	ds_bpermute_b32 v205, v7, v204
	ds_bpermute_b32 v207, v7, v206
	s_waitcnt lgkmcnt(0)
	v_add_f32_e32 v192, v192, v193
	v_add_f32_e32 v194, v194, v195
	v_add_f32_e32 v196, v196, v197
	v_add_f32_e32 v198, v198, v199
	v_add_f32_e32 v200, v200, v201
	v_add_f32_e32 v202, v202, v203
	v_add_f32_e32 v204, v204, v205
	v_add_f32_e32 v206, v206, v207
	ds_bpermute_b32 v193, v8, v192
	ds_bpermute_b32 v195, v8, v194
	ds_bpermute_b32 v197, v8, v196
	ds_bpermute_b32 v199, v8, v198
	ds_bpermute_b32 v201, v8, v200
	ds_bpermute_b32 v203, v8, v202
	ds_bpermute_b32 v205, v8, v204
	ds_bpermute_b32 v207, v8, v206
	s_waitcnt lgkmcnt(0)
	v_add_f32_e32 v192, v192, v193
	v_add_f32_e32 v194, v194, v195
	v_add_f32_e32 v196, v196, v197
	v_add_f32_e32 v198, v198, v199
	v_add_f32_e32 v200, v200, v201
	v_add_f32_e32 v202, v202, v203
	v_add_f32_e32 v204, v204, v205
	v_add_f32_e32 v206, v206, v207
	ds_bpermute_b32 v193, v9, v192
	ds_bpermute_b32 v195, v9, v194
	ds_bpermute_b32 v197, v9, v196
	ds_bpermute_b32 v199, v9, v198
	ds_bpermute_b32 v201, v9, v200
	ds_bpermute_b32 v203, v9, v202
	ds_bpermute_b32 v205, v9, v204
	ds_bpermute_b32 v207, v9, v206
	s_waitcnt lgkmcnt(0)
	v_add_f32_e32 v192, v192, v193
	v_add_f32_e32 v194, v194, v195
	v_add_f32_e32 v196, v196, v197
	v_add_f32_e32 v198, v198, v199
	v_add_f32_e32 v200, v200, v201
	v_add_f32_e32 v202, v202, v203
	v_add_f32_e32 v204, v204, v205
	v_add_f32_e32 v206, v206, v207
	ds_bpermute_b32 v193, v10, v192
	ds_bpermute_b32 v195, v10, v194
	ds_bpermute_b32 v197, v10, v196
	ds_bpermute_b32 v199, v10, v198
	ds_bpermute_b32 v201, v10, v200
	ds_bpermute_b32 v203, v10, v202
	ds_bpermute_b32 v205, v10, v204
	ds_bpermute_b32 v207, v10, v206
	s_waitcnt lgkmcnt(0)
	v_add_f32_e32 v192, v192, v193
	v_add_f32_e32 v194, v194, v195
	v_add_f32_e32 v196, v196, v197
	v_add_f32_e32 v198, v198, v199
	v_add_f32_e32 v200, v200, v201
	v_add_f32_e32 v202, v202, v203
	v_add_f32_e32 v204, v204, v205
	v_add_f32_e32 v206, v206, v207
	ds_bpermute_b32 v193, v11, v192
	ds_bpermute_b32 v195, v11, v194
	ds_bpermute_b32 v197, v11, v196
	ds_bpermute_b32 v199, v11, v198
	ds_bpermute_b32 v201, v11, v200
	ds_bpermute_b32 v203, v11, v202
	ds_bpermute_b32 v205, v11, v204
	ds_bpermute_b32 v207, v11, v206
	s_waitcnt lgkmcnt(0)
	v_add_f32_e32 v192, v192, v193
	v_add_f32_e32 v194, v194, v195
	v_add_f32_e32 v196, v196, v197
	v_add_f32_e32 v198, v198, v199
	v_add_f32_e32 v200, v200, v201
	v_add_f32_e32 v202, v202, v203
	v_add_f32_e32 v204, v204, v205
	v_add_f32_e32 v206, v206, v207
	s_mov_b64 exec, 1
	s_mov_b32 s58, s14
	s_lshl_b32 s59, s58, 2
	s_add_u32 s56, s52, s59
	s_addc_u32 s57, s53, 0
	global_store_dword v12, v192, s[56:57]
	s_add_i32 s58, s58, s99
	s_lshl_b32 s59, s58, 2
	s_add_u32 s56, s52, s59
	s_addc_u32 s57, s53, 0
	global_store_dword v12, v194, s[56:57]
	s_add_i32 s58, s58, s99
	s_lshl_b32 s59, s58, 2
	s_add_u32 s56, s52, s59
	s_addc_u32 s57, s53, 0
	global_store_dword v12, v196, s[56:57]
	s_add_i32 s58, s58, s99
	s_lshl_b32 s59, s58, 2
	s_add_u32 s56, s52, s59
	s_addc_u32 s57, s53, 0
	global_store_dword v12, v198, s[56:57]
	s_add_i32 s58, s58, s99
	s_lshl_b32 s59, s58, 2
	s_add_u32 s56, s52, s59
	s_addc_u32 s57, s53, 0
	global_store_dword v12, v200, s[56:57]
	s_add_i32 s58, s58, s99
	s_lshl_b32 s59, s58, 2
	s_add_u32 s56, s52, s59
	s_addc_u32 s57, s53, 0
	global_store_dword v12, v202, s[56:57]
	s_add_i32 s58, s58, s99
	s_lshl_b32 s59, s58, 2
	s_add_u32 s56, s52, s59
	s_addc_u32 s57, s53, 0
	global_store_dword v12, v204, s[56:57]
	s_add_i32 s58, s58, s99
	s_lshl_b32 s59, s58, 2
	s_add_u32 s56, s52, s59
	s_addc_u32 s57, s53, 0
	global_store_dword v12, v206, s[56:57]
	s_mov_b64 exec, -1
	s_lshl_b32 s15, s99, 3
	s_add_i32 s14, s14, s15
	s_branch .Lxn_loop
.Lxn_try4:
	s_mul_i32 s15, s99, 3
	s_add_i32 s15, s15, s14
	s_cmp_lt_i32 s15, s98
	s_cbranch_scc0 .Lxn_one
	s_mov_b32 s58, s14
	s_add_i32 s60, s58, 0xffffc000
	s_cmpk_lt_i32 s58, 0x4000
	s_cselect_b32 s54, s48, s50
	s_cselect_b32 s55, s49, s51
	s_cselect_b32 s59, s58, s60
	s_lshl_b32 s59, s59, 12
	s_add_u32 s54, s54, s59
	s_addc_u32 s55, s55, 0
	global_load_dwordx4 v[64:67], v4, s[54:55] nt
	global_load_dwordx4 v[68:71], v4, s[54:55] offset:1024 nt
	global_load_dwordx4 v[72:75], v4, s[54:55] offset:2048 nt
	global_load_dwordx4 v[76:79], v4, s[54:55] offset:3072 nt
	s_add_i32 s58, s58, s99
	s_add_i32 s60, s58, 0xffffc000
	s_cmpk_lt_i32 s58, 0x4000
	s_cselect_b32 s54, s48, s50
	s_cselect_b32 s55, s49, s51
	s_cselect_b32 s59, s58, s60
	s_lshl_b32 s59, s59, 12
	s_add_u32 s54, s54, s59
	s_addc_u32 s55, s55, 0
	global_load_dwordx4 v[80:83], v4, s[54:55] nt
	global_load_dwordx4 v[84:87], v4, s[54:55] offset:1024 nt
	global_load_dwordx4 v[88:91], v4, s[54:55] offset:2048 nt
	global_load_dwordx4 v[92:95], v4, s[54:55] offset:3072 nt
	s_add_i32 s58, s58, s99
	s_add_i32 s60, s58, 0xffffc000
	s_cmpk_lt_i32 s58, 0x4000
	s_cselect_b32 s54, s48, s50
	s_cselect_b32 s55, s49, s51
	s_cselect_b32 s59, s58, s60
	s_lshl_b32 s59, s59, 12
	s_add_u32 s54, s54, s59
	s_addc_u32 s55, s55, 0
	global_load_dwordx4 v[96:99], v4, s[54:55] nt
	global_load_dwordx4 v[100:103], v4, s[54:55] offset:1024 nt
	global_load_dwordx4 v[104:107], v4, s[54:55] offset:2048 nt
	global_load_dwordx4 v[108:111], v4, s[54:55] offset:3072 nt
	s_add_i32 s58, s58, s99
	s_add_i32 s60, s58, 0xffffc000
	s_cmpk_lt_i32 s58, 0x4000
	s_cselect_b32 s54, s48, s50
	s_cselect_b32 s55, s49, s51
	s_cselect_b32 s59, s58, s60
	s_lshl_b32 s59, s59, 12
	s_add_u32 s54, s54, s59
	s_addc_u32 s55, s55, 0
	global_load_dwordx4 v[112:115], v4, s[54:55] nt
	global_load_dwordx4 v[116:119], v4, s[54:55] offset:1024 nt
	global_load_dwordx4 v[120:123], v4, s[54:55] offset:2048 nt
	global_load_dwordx4 v[124:127], v4, s[54:55] offset:3072 nt
	s_mov_b32 s58, s14
	s_lshl_b32 s59, s58, 11
	s_add_u32 s56, s46, s59
	s_addc_u32 s57, s47, 0
	s_waitcnt vmcnt(12)
	v_pk_mul_f32 v[192:193], v[64:65], v[64:65]
	v_pk_fma_f32 v[192:193], v[66:67], v[66:67], v[192:193]
	v_pk_fma_f32 v[192:193], v[68:69], v[68:69], v[192:193]
	v_pk_fma_f32 v[192:193], v[70:71], v[70:71], v[192:193]
	v_pk_fma_f32 v[192:193], v[72:73], v[72:73], v[192:193]
	v_pk_fma_f32 v[192:193], v[74:75], v[74:75], v[192:193]
	v_pk_fma_f32 v[192:193], v[76:77], v[76:77], v[192:193]
	v_pk_fma_f32 v[192:193], v[78:79], v[78:79], v[192:193]
	v_cvt_pk_bf16_f32 v64, v64, v65
	v_cvt_pk_bf16_f32 v65, v66, v67
	global_store_dwordx2 v5, v[64:65], s[56:57]
	v_cvt_pk_bf16_f32 v68, v68, v69
	v_cvt_pk_bf16_f32 v69, v70, v71
	global_store_dwordx2 v5, v[68:69], s[56:57] offset:512
	v_cvt_pk_bf16_f32 v72, v72, v73
	v_cvt_pk_bf16_f32 v73, v74, v75
	global_store_dwordx2 v5, v[72:73], s[56:57] offset:1024
	v_cvt_pk_bf16_f32 v76, v76, v77
	v_cvt_pk_bf16_f32 v77, v78, v79
	global_store_dwordx2 v5, v[76:77], s[56:57] offset:1536
	v_add_f32_e32 v192, v192, v193
	s_add_i32 s58, s58, s99
	s_lshl_b32 s59, s58, 11
	s_add_u32 s56, s46, s59
	s_addc_u32 s57, s47, 0
	s_waitcnt vmcnt(12)
	v_pk_mul_f32 v[194:195], v[80:81], v[80:81]
	v_pk_fma_f32 v[194:195], v[82:83], v[82:83], v[194:195]
	v_pk_fma_f32 v[194:195], v[84:85], v[84:85], v[194:195]
	v_pk_fma_f32 v[194:195], v[86:87], v[86:87], v[194:195]
	v_pk_fma_f32 v[194:195], v[88:89], v[88:89], v[194:195]
	v_pk_fma_f32 v[194:195], v[90:91], v[90:91], v[194:195]
	v_pk_fma_f32 v[194:195], v[92:93], v[92:93], v[194:195]
	v_pk_fma_f32 v[194:195], v[94:95], v[94:95], v[194:195]
	v_cvt_pk_bf16_f32 v80, v80, v81
	v_cvt_pk_bf16_f32 v81, v82, v83
	global_store_dwordx2 v5, v[80:81], s[56:57]
	v_cvt_pk_bf16_f32 v84, v84, v85
	v_cvt_pk_bf16_f32 v85, v86, v87
	global_store_dwordx2 v5, v[84:85], s[56:57] offset:512
	v_cvt_pk_bf16_f32 v88, v88, v89
	v_cvt_pk_bf16_f32 v89, v90, v91
	global_store_dwordx2 v5, v[88:89], s[56:57] offset:1024
	v_cvt_pk_bf16_f32 v92, v92, v93
	v_cvt_pk_bf16_f32 v93, v94, v95
	global_store_dwordx2 v5, v[92:93], s[56:57] offset:1536
	v_add_f32_e32 v194, v194, v195
	s_add_i32 s58, s58, s99
	s_lshl_b32 s59, s58, 11
	s_add_u32 s56, s46, s59
	s_addc_u32 s57, s47, 0
	s_waitcnt vmcnt(12)
	v_pk_mul_f32 v[196:197], v[96:97], v[96:97]
	v_pk_fma_f32 v[196:197], v[98:99], v[98:99], v[196:197]
	v_pk_fma_f32 v[196:197], v[100:101], v[100:101], v[196:197]
	v_pk_fma_f32 v[196:197], v[102:103], v[102:103], v[196:197]
	v_pk_fma_f32 v[196:197], v[104:105], v[104:105], v[196:197]
	v_pk_fma_f32 v[196:197], v[106:107], v[106:107], v[196:197]
	v_pk_fma_f32 v[196:197], v[108:109], v[108:109], v[196:197]
	v_pk_fma_f32 v[196:197], v[110:111], v[110:111], v[196:197]
	v_cvt_pk_bf16_f32 v96, v96, v97
	v_cvt_pk_bf16_f32 v97, v98, v99
	global_store_dwordx2 v5, v[96:97], s[56:57]
	v_cvt_pk_bf16_f32 v100, v100, v101
	v_cvt_pk_bf16_f32 v101, v102, v103
	global_store_dwordx2 v5, v[100:101], s[56:57] offset:512
	v_cvt_pk_bf16_f32 v104, v104, v105
	v_cvt_pk_bf16_f32 v105, v106, v107
	global_store_dwordx2 v5, v[104:105], s[56:57] offset:1024
	v_cvt_pk_bf16_f32 v108, v108, v109
	v_cvt_pk_bf16_f32 v109, v110, v111
	global_store_dwordx2 v5, v[108:109], s[56:57] offset:1536
	v_add_f32_e32 v196, v196, v197
	s_add_i32 s58, s58, s99
	s_lshl_b32 s59, s58, 11
	s_add_u32 s56, s46, s59
	s_addc_u32 s57, s47, 0
	s_waitcnt vmcnt(12)
	v_pk_mul_f32 v[198:199], v[112:113], v[112:113]
	v_pk_fma_f32 v[198:199], v[114:115], v[114:115], v[198:199]
	v_pk_fma_f32 v[198:199], v[116:117], v[116:117], v[198:199]
	v_pk_fma_f32 v[198:199], v[118:119], v[118:119], v[198:199]
	v_pk_fma_f32 v[198:199], v[120:121], v[120:121], v[198:199]
	v_pk_fma_f32 v[198:199], v[122:123], v[122:123], v[198:199]
	v_pk_fma_f32 v[198:199], v[124:125], v[124:125], v[198:199]
	v_pk_fma_f32 v[198:199], v[126:127], v[126:127], v[198:199]
	v_cvt_pk_bf16_f32 v112, v112, v113
	v_cvt_pk_bf16_f32 v113, v114, v115
	global_store_dwordx2 v5, v[112:113], s[56:57]
	v_cvt_pk_bf16_f32 v116, v116, v117
	v_cvt_pk_bf16_f32 v117, v118, v119
	global_store_dwordx2 v5, v[116:117], s[56:57] offset:512
	v_cvt_pk_bf16_f32 v120, v120, v121
	v_cvt_pk_bf16_f32 v121, v122, v123
	global_store_dwordx2 v5, v[120:121], s[56:57] offset:1024
	v_cvt_pk_bf16_f32 v124, v124, v125
	v_cvt_pk_bf16_f32 v125, v126, v127
	global_store_dwordx2 v5, v[124:125], s[56:57] offset:1536
	v_add_f32_e32 v198, v198, v199
	ds_bpermute_b32 v193, v6, v192
	ds_bpermute_b32 v195, v6, v194
	ds_bpermute_b32 v197, v6, v196
	ds_bpermute_b32 v199, v6, v198
	s_waitcnt lgkmcnt(0)
	v_add_f32_e32 v192, v192, v193
	v_add_f32_e32 v194, v194, v195
	v_add_f32_e32 v196, v196, v197
	v_add_f32_e32 v198, v198, v199
	ds_bpermute_b32 v193, v7, v192
	ds_bpermute_b32 v195, v7, v194
	ds_bpermute_b32 v197, v7, v196
	ds_bpermute_b32 v199, v7, v198
	s_waitcnt lgkmcnt(0)
	v_add_f32_e32 v192, v192, v193
	v_add_f32_e32 v194, v194, v195
	v_add_f32_e32 v196, v196, v197
	v_add_f32_e32 v198, v198, v199
	ds_bpermute_b32 v193, v8, v192
	ds_bpermute_b32 v195, v8, v194
	ds_bpermute_b32 v197, v8, v196
	ds_bpermute_b32 v199, v8, v198
	s_waitcnt lgkmcnt(0)
	v_add_f32_e32 v192, v192, v193
	v_add_f32_e32 v194, v194, v195
	v_add_f32_e32 v196, v196, v197
	v_add_f32_e32 v198, v198, v199
	ds_bpermute_b32 v193, v9, v192
	ds_bpermute_b32 v195, v9, v194
	ds_bpermute_b32 v197, v9, v196
	ds_bpermute_b32 v199, v9, v198
	s_waitcnt lgkmcnt(0)
	v_add_f32_e32 v192, v192, v193
	v_add_f32_e32 v194, v194, v195
	v_add_f32_e32 v196, v196, v197
	v_add_f32_e32 v198, v198, v199
	ds_bpermute_b32 v193, v10, v192
	ds_bpermute_b32 v195, v10, v194
	ds_bpermute_b32 v197, v10, v196
	ds_bpermute_b32 v199, v10, v198
	s_waitcnt lgkmcnt(0)
	v_add_f32_e32 v192, v192, v193
	v_add_f32_e32 v194, v194, v195
	v_add_f32_e32 v196, v196, v197
	v_add_f32_e32 v198, v198, v199
	ds_bpermute_b32 v193, v11, v192
	ds_bpermute_b32 v195, v11, v194
	ds_bpermute_b32 v197, v11, v196
	ds_bpermute_b32 v199, v11, v198
	s_waitcnt lgkmcnt(0)
	v_add_f32_e32 v192, v192, v193
	v_add_f32_e32 v194, v194, v195
	v_add_f32_e32 v196, v196, v197
	v_add_f32_e32 v198, v198, v199
	s_mov_b64 exec, 1
	s_mov_b32 s58, s14
	s_lshl_b32 s59, s58, 2
	s_add_u32 s56, s52, s59
	s_addc_u32 s57, s53, 0
	global_store_dword v12, v192, s[56:57]
	s_add_i32 s58, s58, s99
	s_lshl_b32 s59, s58, 2
	s_add_u32 s56, s52, s59
	s_addc_u32 s57, s53, 0
	global_store_dword v12, v194, s[56:57]
	s_add_i32 s58, s58, s99
	s_lshl_b32 s59, s58, 2
	s_add_u32 s56, s52, s59
	s_addc_u32 s57, s53, 0
	global_store_dword v12, v196, s[56:57]
	s_add_i32 s58, s58, s99
	s_lshl_b32 s59, s58, 2
	s_add_u32 s56, s52, s59
	s_addc_u32 s57, s53, 0
	global_store_dword v12, v198, s[56:57]
	s_mov_b64 exec, -1
	s_lshl_b32 s15, s99, 2
	s_add_i32 s14, s14, s15
	s_branch .Lxn_loop
.Lxn_one:
	s_mov_b32 s58, s14
	s_add_i32 s60, s58, 0xffffc000
	s_cmpk_lt_i32 s58, 0x4000
	s_cselect_b32 s54, s48, s50
	s_cselect_b32 s55, s49, s51
	s_cselect_b32 s59, s58, s60
	s_lshl_b32 s59, s59, 12
	s_add_u32 s54, s54, s59
	s_addc_u32 s55, s55, 0
	global_load_dwordx4 v[64:67], v4, s[54:55] nt
	global_load_dwordx4 v[68:71], v4, s[54:55] offset:1024 nt
	global_load_dwordx4 v[72:75], v4, s[54:55] offset:2048 nt
	global_load_dwordx4 v[76:79], v4, s[54:55] offset:3072 nt
	s_mov_b32 s58, s14
	s_lshl_b32 s59, s58, 11
	s_add_u32 s56, s46, s59
	s_addc_u32 s57, s47, 0
	s_waitcnt vmcnt(0)
	v_pk_mul_f32 v[192:193], v[64:65], v[64:65]
	v_pk_fma_f32 v[192:193], v[66:67], v[66:67], v[192:193]
	v_pk_fma_f32 v[192:193], v[68:69], v[68:69], v[192:193]
	v_pk_fma_f32 v[192:193], v[70:71], v[70:71], v[192:193]
	v_pk_fma_f32 v[192:193], v[72:73], v[72:73], v[192:193]
	v_pk_fma_f32 v[192:193], v[74:75], v[74:75], v[192:193]
	v_pk_fma_f32 v[192:193], v[76:77], v[76:77], v[192:193]
	v_pk_fma_f32 v[192:193], v[78:79], v[78:79], v[192:193]
	v_cvt_pk_bf16_f32 v64, v64, v65
	v_cvt_pk_bf16_f32 v65, v66, v67
	global_store_dwordx2 v5, v[64:65], s[56:57]
	v_cvt_pk_bf16_f32 v68, v68, v69
	v_cvt_pk_bf16_f32 v69, v70, v71
	global_store_dwordx2 v5, v[68:69], s[56:57] offset:512
	v_cvt_pk_bf16_f32 v72, v72, v73
	v_cvt_pk_bf16_f32 v73, v74, v75
	global_store_dwordx2 v5, v[72:73], s[56:57] offset:1024
	v_cvt_pk_bf16_f32 v76, v76, v77
	v_cvt_pk_bf16_f32 v77, v78, v79
	global_store_dwordx2 v5, v[76:77], s[56:57] offset:1536
	v_add_f32_e32 v192, v192, v193
	ds_bpermute_b32 v193, v6, v192
	s_waitcnt lgkmcnt(0)
	v_add_f32_e32 v192, v192, v193
	ds_bpermute_b32 v193, v7, v192
	s_waitcnt lgkmcnt(0)
	v_add_f32_e32 v192, v192, v193
	ds_bpermute_b32 v193, v8, v192
	s_waitcnt lgkmcnt(0)
	v_add_f32_e32 v192, v192, v193
	ds_bpermute_b32 v193, v9, v192
	s_waitcnt lgkmcnt(0)
	v_add_f32_e32 v192, v192, v193
	ds_bpermute_b32 v193, v10, v192
	s_waitcnt lgkmcnt(0)
	v_add_f32_e32 v192, v192, v193
	ds_bpermute_b32 v193, v11, v192
	s_waitcnt lgkmcnt(0)
	v_add_f32_e32 v192, v192, v193
	s_mov_b64 exec, 1
	s_mov_b32 s58, s14
	s_lshl_b32 s59, s58, 2
	s_add_u32 s56, s52, s59
	s_addc_u32 s57, s53, 0
	global_store_dword v12, v192, s[56:57]
	s_mov_b64 exec, -1
	s_add_i32 s14, s14, s99
	s_branch .Lxn_loop

.LBB0_441:
	s_or_b64 exec, exec, s[40:41]
	s_xor_b64 s[0:1], s[62:63], -1
	v_writelane_b32 v252, s0, 48
	s_mov_b32 s37, s93
	s_andn2_b64 vcc, exec, s[66:67]
	v_writelane_b32 v252, s1, 49
	s_waitcnt lgkmcnt(0)
	s_barrier
	s_cbranch_vccnz .LBB0_531
	v_readlane_b32 s98, v252, 47
	s_cmp_lg_u32 s98, 0
	s_cbranch_scc1 .Lw1_skip
	s_cmpk_lg_u32 s78, 0x100
	s_cbranch_scc1 .Lw1_skip
	s_cmpk_lt_u32 s2, 0x80
	s_cbranch_scc1 .Lw1_skip
	v_writelane_b32 v254, s8, 0
	v_writelane_b32 v254, s9, 1
	v_writelane_b32 v254, s10, 2
	v_writelane_b32 v254, s11, 3
	v_writelane_b32 v254, s12, 4
	v_writelane_b32 v254, s13, 5
	v_writelane_b32 v254, s14, 6
	v_writelane_b32 v254, s15, 7
	v_writelane_b32 v254, s16, 8
	v_writelane_b32 v254, s17, 9
	v_writelane_b32 v254, s18, 10
	v_writelane_b32 v254, s19, 11
	v_writelane_b32 v254, s20, 12
	v_writelane_b32 v254, s21, 13
	v_writelane_b32 v254, s22, 14
	v_writelane_b32 v254, s23, 15
	v_writelane_b32 v254, s24, 16
	v_writelane_b32 v254, s25, 17
	v_writelane_b32 v254, s26, 18
	v_writelane_b32 v254, s27, 19
	v_writelane_b32 v254, s28, 20
	v_writelane_b32 v254, s29, 21
	v_writelane_b32 v254, s30, 22
	v_writelane_b32 v254, s31, 23
	v_writelane_b32 v254, s32, 24
	v_writelane_b32 v254, s33, 25
	v_writelane_b32 v254, s34, 26
	v_writelane_b32 v254, s35, 27
	v_writelane_b32 v254, s40, 28
	v_writelane_b32 v254, s41, 29
	v_writelane_b32 v254, s42, 30
	v_writelane_b32 v254, s43, 31
	v_writelane_b32 v254, s44, 32
	v_writelane_b32 v254, s45, 33
	v_writelane_b32 v254, s46, 34
	v_writelane_b32 v254, s47, 35
	v_writelane_b32 v254, s48, 36
	v_writelane_b32 v254, s49, 37
	v_writelane_b32 v254, s50, 38
	v_writelane_b32 v254, s51, 39
	v_writelane_b32 v254, s52, 40
	v_writelane_b32 v254, s53, 41
	v_writelane_b32 v254, s54, 42
	v_writelane_b32 v254, s55, 43
	v_writelane_b32 v254, s56, 44
	v_writelane_b32 v254, s57, 45
	v_writelane_b32 v254, s58, 46
	v_writelane_b32 v254, s59, 47
	v_writelane_b32 v254, s60, 48
	v_writelane_b32 v254, s61, 49
	v_writelane_b32 v254, s62, 50
	v_writelane_b32 v254, s63, 51
	v_writelane_b32 v254, s66, 52
	v_writelane_b32 v254, s67, 53
	v_writelane_b32 v254, s68, 54
	v_writelane_b32 v254, s69, 55
	v_writelane_b32 v254, s70, 56
	v_writelane_b32 v254, s71, 57
	v_writelane_b32 v254, s72, 58
	v_writelane_b32 v254, s73, 59
	v_writelane_b32 v254, s74, 60
	v_writelane_b32 v254, s75, 61
	v_writelane_b32 v254, s76, 62
	v_writelane_b32 v254, s77, 63
	v_writelane_b32 v255, s80, 0
	v_writelane_b32 v255, s81, 1
	v_writelane_b32 v255, s82, 2
	v_writelane_b32 v255, s83, 3
	v_writelane_b32 v255, s84, 4
	v_writelane_b32 v255, s85, 5
	v_writelane_b32 v255, s86, 6
	v_writelane_b32 v255, s87, 7
	v_writelane_b32 v255, s88, 8
	v_writelane_b32 v255, s89, 9
	v_writelane_b32 v255, s90, 10
	v_writelane_b32 v255, s91, 11
	v_writelane_b32 v255, s92, 12
	v_writelane_b32 v255, s93, 13
	v_writelane_b32 v255, s94, 14
	v_writelane_b32 v255, s95, 15
	v_and_b32_e32 v207, 31, v227
	v_lshlrev_b32_e32 v200, 4, v207
	v_lshrrev_b32_e32 v201, 5, v227
	v_lshlrev_b32_e32 v202, 2, v207
	v_and_b32_e32 v203, 64, v202
	v_add_u32_e32 v203, v203, v202
	v_lshlrev_b32_e32 v204, 5, v201
	v_readlane_b32 s8, v253, 36
	v_readlane_b32 s9, v253, 37
	v_readlane_b32 s10, v253, 34
	v_readlane_b32 s11, v253, 35
	v_readlane_b32 s12, v253, 16
	v_readlane_b32 s13, v253, 17
	v_readlane_b32 s14, v253, 18
	v_readlane_b32 s15, v253, 19
	v_readlane_b32 s16, v253, 20
	v_readlane_b32 s17, v253, 21
	v_readlane_b32 s18, v253, 22
	v_readlane_b32 s19, v253, 23
	v_readfirstlane_b32 s66, v226
	s_lshr_b32 s66, s66, 6
	s_add_i32 s67, s2, 0xffffff80
	s_lshl_b32 s67, s67, 3
	s_add_i32 s66, s66, s67
	s_addk_i32 s66, 0xc00
	s_add_i32 s68, s66, 0x400
	s_add_i32 s67, s66, 0x800
	s_cmpk_ge_i32 s66, 0xc00
	s_cselect_b32 s0, 1, 0
	s_mul_i32 s1, s0, 0xc00
	s_sub_i32 s1, s66, s1
	s_mul_i32 s4, s0, 0x1800000
	s_add_u32 s70, s64, s4
	s_addc_u32 s71, s65, 0
	s_lshl_b32 s69, s0, 12
	s_cmpk_lt_i32 s1, 0x300
	s_cbranch_scc1 .Lw1_in_1
	s_cmpk_lt_i32 s1, 0x400
	s_cbranch_scc1 .Lw1_out_1
	s_cmpk_lt_i32 s1, 0x800
	s_cbranch_scc1 .Lw1_up_1
	s_sub_i32 s1, s1, 0x800
	s_lshr_b32 s72, s1, 3
	s_and_b32 s73, s1, 7
	s_movk_i32 s74, 0x400
	s_mul_i32 s4, s0, 0x1000000
	s_add_u32 s76, s18, s4
	s_addc_u32 s77, s19, 0
	s_mov_b32 s4, 0x1000000
	s_lshl_b32 s5, s73, 7
	s_movk_i32 s27, 0xd00
	s_branch .Lw1_join_1

.Lw1_join_1:
	s_mul_i32 s0, s72, s74
	s_lshl_b32 s0, s0, 5
	s_lshl_b32 s1, s73, 7
	s_add_i32 s0, s0, s1
	s_lshl_b32 s0, s0, 2
	s_add_u32 s20, s76, s0
	s_addc_u32 s21, s77, 0
	s_lshl_b32 s26, s74, 2
	s_lshr_b32 s0, s27, 8
	s_lshl_b32 s0, s5, s0
	s_add_i32 s0, s0, s4
	s_lshl_b32 s1, s72, 6
	s_add_i32 s0, s0, s1
	s_add_u32 s22, s70, s0
	s_addc_u32 s23, s71, 0
	s_lshl_b32 s1, s72, 7
	s_add_u32 s24, s24, s1
	s_addc_u32 s25, s25, 0
	s_lshl_b32 s0, s26, 4
	v_mad_u32_u24 v205, v201, s0, v200
	global_load_dwordx4 v[8:11], v205, s[20:21] nt
	s_add_u32 s20, s20, s26
	s_addc_u32 s21, s21, 0
	global_load_dwordx4 v[12:15], v205, s[20:21] nt
	s_add_u32 s20, s20, s26
	s_addc_u32 s21, s21, 0
	global_load_dwordx4 v[16:19], v205, s[20:21] nt
	s_add_u32 s20, s20, s26
	s_addc_u32 s21, s21, 0
	global_load_dwordx4 v[20:23], v205, s[20:21] nt
	s_add_u32 s20, s20, s26
	s_addc_u32 s21, s21, 0
	global_load_dwordx4 v[24:27], v205, s[20:21] nt
	s_add_u32 s20, s20, s26
	s_addc_u32 s21, s21, 0
	global_load_dwordx4 v[28:31], v205, s[20:21] nt
	s_add_u32 s20, s20, s26
	s_addc_u32 s21, s21, 0
	global_load_dwordx4 v[32:35], v205, s[20:21] nt
	s_add_u32 s20, s20, s26
	s_addc_u32 s21, s21, 0
	global_load_dwordx4 v[36:39], v205, s[20:21] nt
	s_add_u32 s20, s20, s26
	s_addc_u32 s21, s21, 0
	global_load_dwordx4 v[40:43], v205, s[20:21] nt
	s_add_u32 s20, s20, s26
	s_addc_u32 s21, s21, 0
	global_load_dwordx4 v[44:47], v205, s[20:21] nt
	s_add_u32 s20, s20, s26
	s_addc_u32 s21, s21, 0
	global_load_dwordx4 v[48:51], v205, s[20:21] nt
	s_add_u32 s20, s20, s26
	s_addc_u32 s21, s21, 0
	global_load_dwordx4 v[52:55], v205, s[20:21] nt
	s_add_u32 s20, s20, s26
	s_addc_u32 s21, s21, 0
	global_load_dwordx4 v[56:59], v205, s[20:21] nt
	s_add_u32 s20, s20, s26
	s_addc_u32 s21, s21, 0
	global_load_dwordx4 v[60:63], v205, s[20:21] nt
	s_add_u32 s20, s20, s26
	s_addc_u32 s21, s21, 0
	global_load_dwordx4 v[64:67], v205, s[20:21] nt
	s_add_u32 s20, s20, s26
	s_addc_u32 s21, s21, 0
	global_load_dwordx4 v[68:71], v205, s[20:21] nt
	s_cmpk_ge_i32 s68, 0xc00
	s_cselect_b32 s0, 1, 0
	s_mul_i32 s1, s0, 0xc00
	s_sub_i32 s1, s68, s1
	s_mul_i32 s4, s0, 0x1800000
	s_add_u32 s70, s64, s4
	s_addc_u32 s71, s65, 0
	s_lshl_b32 s69, s0, 12
	s_cmpk_lt_i32 s1, 0x300
	s_cbranch_scc1 .Lw1_in_2
	s_cmpk_lt_i32 s1, 0x400
	s_cbranch_scc1 .Lw1_out_2
	s_cmpk_lt_i32 s1, 0x800
	s_cbranch_scc1 .Lw1_up_2
	s_sub_i32 s1, s1, 0x800
	s_lshr_b32 s72, s1, 3
	s_and_b32 s73, s1, 7
	s_movk_i32 s74, 0x400
	s_mul_i32 s4, s0, 0x1000000
	s_add_u32 s76, s18, s4
	s_addc_u32 s77, s19, 0
	s_mov_b32 s4, 0x1000000
	s_lshl_b32 s5, s73, 7
	s_movk_i32 s35, 0xd00
	s_branch .Lw1_join_2

.Lw1_join_2:
	s_mul_i32 s0, s72, s74
	s_lshl_b32 s0, s0, 5
	s_lshl_b32 s1, s73, 7
	s_add_i32 s0, s0, s1
	s_lshl_b32 s0, s0, 2
	s_add_u32 s28, s76, s0
	s_addc_u32 s29, s77, 0
	s_lshl_b32 s34, s74, 2
	s_lshr_b32 s0, s35, 8
	s_lshl_b32 s0, s5, s0
	s_add_i32 s0, s0, s4
	s_lshl_b32 s1, s72, 6
	s_add_i32 s0, s0, s1
	s_add_u32 s30, s70, s0
	s_addc_u32 s31, s71, 0
	s_lshl_b32 s1, s72, 7
	s_add_u32 s32, s32, s1
	s_addc_u32 s33, s33, 0
	s_lshl_b32 s0, s34, 4
	v_mad_u32_u24 v205, v201, s0, v200
	global_load_dwordx4 v[72:75], v205, s[28:29] nt
	s_add_u32 s28, s28, s34
	s_addc_u32 s29, s29, 0
	global_load_dwordx4 v[76:79], v205, s[28:29] nt
	s_add_u32 s28, s28, s34
	s_addc_u32 s29, s29, 0
	global_load_dwordx4 v[80:83], v205, s[28:29] nt
	s_add_u32 s28, s28, s34
	s_addc_u32 s29, s29, 0
	global_load_dwordx4 v[84:87], v205, s[28:29] nt
	s_add_u32 s28, s28, s34
	s_addc_u32 s29, s29, 0
	global_load_dwordx4 v[88:91], v205, s[28:29] nt
	s_add_u32 s28, s28, s34
	s_addc_u32 s29, s29, 0
	global_load_dwordx4 v[92:95], v205, s[28:29] nt
	s_add_u32 s28, s28, s34
	s_addc_u32 s29, s29, 0
	global_load_dwordx4 v[96:99], v205, s[28:29] nt
	s_add_u32 s28, s28, s34
	s_addc_u32 s29, s29, 0
	global_load_dwordx4 v[100:103], v205, s[28:29] nt
	s_add_u32 s28, s28, s34
	s_addc_u32 s29, s29, 0
	global_load_dwordx4 v[104:107], v205, s[28:29] nt
	s_add_u32 s28, s28, s34
	s_addc_u32 s29, s29, 0
	global_load_dwordx4 v[108:111], v205, s[28:29] nt
	s_add_u32 s28, s28, s34
	s_addc_u32 s29, s29, 0
	global_load_dwordx4 v[112:115], v205, s[28:29] nt
	s_add_u32 s28, s28, s34
	s_addc_u32 s29, s29, 0
	global_load_dwordx4 v[116:119], v205, s[28:29] nt
	s_add_u32 s28, s28, s34
	s_addc_u32 s29, s29, 0
	global_load_dwordx4 v[120:123], v205, s[28:29] nt
	s_add_u32 s28, s28, s34
	s_addc_u32 s29, s29, 0
	global_load_dwordx4 v[124:127], v205, s[28:29] nt
	s_add_u32 s28, s28, s34
	s_addc_u32 s29, s29, 0
	global_load_dwordx4 v[128:131], v205, s[28:29] nt
	s_add_u32 s28, s28, s34
	s_addc_u32 s29, s29, 0
	global_load_dwordx4 v[132:135], v205, s[28:29] nt
	s_cmpk_ge_i32 s67, 0xc00
	s_cselect_b32 s0, 1, 0
	s_mul_i32 s1, s0, 0xc00
	s_sub_i32 s1, s67, s1
	s_mul_i32 s4, s0, 0x1800000
	s_add_u32 s70, s64, s4
	s_addc_u32 s71, s65, 0
	s_lshl_b32 s69, s0, 12
	s_cmpk_lt_i32 s1, 0x300
	s_cbranch_scc1 .Lw1_in_3
	s_cmpk_lt_i32 s1, 0x400
	s_cbranch_scc1 .Lw1_out_3
	s_cmpk_lt_i32 s1, 0x800
	s_cbranch_scc1 .Lw1_up_3
	s_sub_i32 s1, s1, 0x800
	s_lshr_b32 s72, s1, 3
	s_and_b32 s73, s1, 7
	s_movk_i32 s74, 0x400
	s_mul_i32 s4, s0, 0x1000000
	s_add_u32 s76, s18, s4
	s_addc_u32 s77, s19, 0
	s_mov_b32 s4, 0x1000000
	s_lshl_b32 s5, s73, 7
	s_movk_i32 s47, 0xd00
	s_branch .Lw1_join_3

.Lw1_join_3:
	s_mul_i32 s0, s72, s74
	s_lshl_b32 s0, s0, 5
	s_lshl_b32 s1, s73, 7
	s_add_i32 s0, s0, s1
	s_lshl_b32 s0, s0, 2
	s_add_u32 s40, s76, s0
	s_addc_u32 s41, s77, 0
	s_lshl_b32 s46, s74, 2
	s_lshr_b32 s0, s47, 8
	s_lshl_b32 s0, s5, s0
	s_add_i32 s0, s0, s4
	s_lshl_b32 s1, s72, 6
	s_add_i32 s0, s0, s1
	s_add_u32 s42, s70, s0
	s_addc_u32 s43, s71, 0
	s_lshl_b32 s1, s72, 7
	s_add_u32 s44, s44, s1
	s_addc_u32 s45, s45, 0
	s_lshl_b32 s0, s46, 4
	v_mad_u32_u24 v205, v201, s0, v200
	global_load_dwordx4 v[136:139], v205, s[40:41] nt
	s_add_u32 s40, s40, s46
	s_addc_u32 s41, s41, 0
	global_load_dwordx4 v[140:143], v205, s[40:41] nt
	s_add_u32 s40, s40, s46
	s_addc_u32 s41, s41, 0
	global_load_dwordx4 v[144:147], v205, s[40:41] nt
	s_add_u32 s40, s40, s46
	s_addc_u32 s41, s41, 0
	global_load_dwordx4 v[148:151], v205, s[40:41] nt
	s_add_u32 s40, s40, s46
	s_addc_u32 s41, s41, 0
	global_load_dwordx4 v[152:155], v205, s[40:41] nt
	s_add_u32 s40, s40, s46
	s_addc_u32 s41, s41, 0
	global_load_dwordx4 v[156:159], v205, s[40:41] nt
	s_add_u32 s40, s40, s46
	s_addc_u32 s41, s41, 0
	global_load_dwordx4 v[160:163], v205, s[40:41] nt
	s_add_u32 s40, s40, s46
	s_addc_u32 s41, s41, 0
	global_load_dwordx4 v[164:167], v205, s[40:41] nt
	s_add_u32 s40, s40, s46
	s_addc_u32 s41, s41, 0
	global_load_dwordx4 v[168:171], v205, s[40:41] nt
	s_add_u32 s40, s40, s46
	s_addc_u32 s41, s41, 0
	global_load_dwordx4 v[172:175], v205, s[40:41] nt
	s_add_u32 s40, s40, s46
	s_addc_u32 s41, s41, 0
	global_load_dwordx4 v[176:179], v205, s[40:41] nt
	s_add_u32 s40, s40, s46
	s_addc_u32 s41, s41, 0
	global_load_dwordx4 v[180:183], v205, s[40:41] nt
	s_add_u32 s40, s40, s46
	s_addc_u32 s41, s41, 0
	global_load_dwordx4 v[184:187], v205, s[40:41] nt
	s_add_u32 s40, s40, s46
	s_addc_u32 s41, s41, 0
	global_load_dwordx4 v[188:191], v205, s[40:41] nt
	s_add_u32 s40, s40, s46
	s_addc_u32 s41, s41, 0
	global_load_dwordx4 v[192:195], v205, s[40:41] nt
	s_add_u32 s40, s40, s46
	s_addc_u32 s41, s41, 0
	global_load_dwordx4 v[196:199], v205, s[40:41] nt
	s_bitcmp1_b32 s27, 0
	s_cbranch_scc0 .Lw1_nog_4
	s_load_dwordx16 s[80:95], s[24:25], 0x0
	s_load_dwordx16 s[48:63], s[24:25], 0x40
.Lw1_nog_4:
	s_bitcmp1_b32 s27, 1
	s_cselect_b64 vcc, -1, 0
	s_lshr_b32 s0, s27, 8
	s_lshl_b32 s4, 1, s0
	v_cndmask_b32_e32 v207, v202, v203, vcc
	v_lshlrev_b32_e32 v206, s0, v207
	v_add_u32_e32 v206, v206, v204
	s_waitcnt vmcnt(32)
	s_bitcmp1_b32 s27, 0
	s_cbranch_scc0 .Lw1_nomul_4
	s_waitcnt lgkmcnt(0)
	s_mov_b32 exec_hi, 0
	v_mul_f32_e32 v8, s80, v8
	v_mul_f32_e32 v9, s80, v9
	v_mul_f32_e32 v10, s80, v10
	v_mul_f32_e32 v11, s80, v11
	v_mul_f32_e32 v12, s81, v12
	v_mul_f32_e32 v13, s81, v13
	v_mul_f32_e32 v14, s81, v14
	v_mul_f32_e32 v15, s81, v15
	v_mul_f32_e32 v16, s82, v16
	v_mul_f32_e32 v17, s82, v17
	v_mul_f32_e32 v18, s82, v18
	v_mul_f32_e32 v19, s82, v19
	v_mul_f32_e32 v20, s83, v20
	v_mul_f32_e32 v21, s83, v21
	v_mul_f32_e32 v22, s83, v22
	v_mul_f32_e32 v23, s83, v23
	v_mul_f32_e32 v24, s84, v24
	v_mul_f32_e32 v25, s84, v25
	v_mul_f32_e32 v26, s84, v26
	v_mul_f32_e32 v27, s84, v27
	v_mul_f32_e32 v28, s85, v28
	v_mul_f32_e32 v29, s85, v29
	v_mul_f32_e32 v30, s85, v30
	v_mul_f32_e32 v31, s85, v31
	v_mul_f32_e32 v32, s86, v32
	v_mul_f32_e32 v33, s86, v33
	v_mul_f32_e32 v34, s86, v34
	v_mul_f32_e32 v35, s86, v35
	v_mul_f32_e32 v36, s87, v36
	v_mul_f32_e32 v37, s87, v37
	v_mul_f32_e32 v38, s87, v38
	v_mul_f32_e32 v39, s87, v39
	v_mul_f32_e32 v40, s88, v40
	v_mul_f32_e32 v41, s88, v41
	v_mul_f32_e32 v42, s88, v42
	v_mul_f32_e32 v43, s88, v43
	v_mul_f32_e32 v44, s89, v44
	v_mul_f32_e32 v45, s89, v45
	v_mul_f32_e32 v46, s89, v46
	v_mul_f32_e32 v47, s89, v47
	v_mul_f32_e32 v48, s90, v48
	v_mul_f32_e32 v49, s90, v49
	v_mul_f32_e32 v50, s90, v50
	v_mul_f32_e32 v51, s90, v51
	v_mul_f32_e32 v52, s91, v52
	v_mul_f32_e32 v53, s91, v53
	v_mul_f32_e32 v54, s91, v54
	v_mul_f32_e32 v55, s91, v55
	v_mul_f32_e32 v56, s92, v56
	v_mul_f32_e32 v57, s92, v57
	v_mul_f32_e32 v58, s92, v58
	v_mul_f32_e32 v59, s92, v59
	v_mul_f32_e32 v60, s93, v60
	v_mul_f32_e32 v61, s93, v61
	v_mul_f32_e32 v62, s93, v62
	v_mul_f32_e32 v63, s93, v63
	v_mul_f32_e32 v64, s94, v64
	v_mul_f32_e32 v65, s94, v65
	v_mul_f32_e32 v66, s94, v66
	v_mul_f32_e32 v67, s94, v67
	v_mul_f32_e32 v68, s95, v68
	v_mul_f32_e32 v69, s95, v69
	v_mul_f32_e32 v70, s95, v70
	v_mul_f32_e32 v71, s95, v71
	s_mov_b32 exec_lo, 0
	s_mov_b32 exec_hi, -1
	v_mul_f32_e32 v8, s48, v8
	v_mul_f32_e32 v9, s48, v9
	v_mul_f32_e32 v10, s48, v10
	v_mul_f32_e32 v11, s48, v11
	v_mul_f32_e32 v12, s49, v12
	v_mul_f32_e32 v13, s49, v13
	v_mul_f32_e32 v14, s49, v14
	v_mul_f32_e32 v15, s49, v15
	v_mul_f32_e32 v16, s50, v16
	v_mul_f32_e32 v17, s50, v17
	v_mul_f32_e32 v18, s50, v18
	v_mul_f32_e32 v19, s50, v19
	v_mul_f32_e32 v20, s51, v20
	v_mul_f32_e32 v21, s51, v21
	v_mul_f32_e32 v22, s51, v22
	v_mul_f32_e32 v23, s51, v23
	v_mul_f32_e32 v24, s52, v24
	v_mul_f32_e32 v25, s52, v25
	v_mul_f32_e32 v26, s52, v26
	v_mul_f32_e32 v27, s52, v27
	v_mul_f32_e32 v28, s53, v28
	v_mul_f32_e32 v29, s53, v29
	v_mul_f32_e32 v30, s53, v30
	v_mul_f32_e32 v31, s53, v31
	v_mul_f32_e32 v32, s54, v32
	v_mul_f32_e32 v33, s54, v33
	v_mul_f32_e32 v34, s54, v34
	v_mul_f32_e32 v35, s54, v35
	v_mul_f32_e32 v36, s55, v36
	v_mul_f32_e32 v37, s55, v37
	v_mul_f32_e32 v38, s55, v38
	v_mul_f32_e32 v39, s55, v39
	v_mul_f32_e32 v40, s56, v40
	v_mul_f32_e32 v41, s56, v41
	v_mul_f32_e32 v42, s56, v42
	v_mul_f32_e32 v43, s56, v43
	v_mul_f32_e32 v44, s57, v44
	v_mul_f32_e32 v45, s57, v45
	v_mul_f32_e32 v46, s57, v46
	v_mul_f32_e32 v47, s57, v47
	v_mul_f32_e32 v48, s58, v48
	v_mul_f32_e32 v49, s58, v49
	v_mul_f32_e32 v50, s58, v50
	v_mul_f32_e32 v51, s58, v51
	v_mul_f32_e32 v52, s59, v52
	v_mul_f32_e32 v53, s59, v53
	v_mul_f32_e32 v54, s59, v54
	v_mul_f32_e32 v55, s59, v55
	v_mul_f32_e32 v56, s60, v56
	v_mul_f32_e32 v57, s60, v57
	v_mul_f32_e32 v58, s60, v58
	v_mul_f32_e32 v59, s60, v59
	v_mul_f32_e32 v60, s61, v60
	v_mul_f32_e32 v61, s61, v61
	v_mul_f32_e32 v62, s61, v62
	v_mul_f32_e32 v63, s61, v63
	v_mul_f32_e32 v64, s62, v64
	v_mul_f32_e32 v65, s62, v65
	v_mul_f32_e32 v66, s62, v66
	v_mul_f32_e32 v67, s62, v67
	v_mul_f32_e32 v68, s63, v68
	v_mul_f32_e32 v69, s63, v69
	v_mul_f32_e32 v70, s63, v70
	v_mul_f32_e32 v71, s63, v71
	s_mov_b64 exec, -1
.Lw1_nomul_4:
	v_cvt_pk_bf16_f32 v236, v8, v12
	v_cvt_pk_bf16_f32 v237, v16, v20
	v_cvt_pk_bf16_f32 v238, v24, v28
	v_cvt_pk_bf16_f32 v239, v32, v36
	global_store_dwordx4 v206, v[236:239], s[22:23]
	v_cvt_pk_bf16_f32 v240, v40, v44
	v_cvt_pk_bf16_f32 v241, v48, v52
	v_cvt_pk_bf16_f32 v242, v56, v60
	v_cvt_pk_bf16_f32 v243, v64, v68
	global_store_dwordx4 v206, v[240:243], s[22:23] offset:16
	s_add_u32 s22, s22, s4
	s_addc_u32 s23, s23, 0
	v_cvt_pk_bf16_f32 v244, v9, v13
	v_cvt_pk_bf16_f32 v245, v17, v21
	v_cvt_pk_bf16_f32 v246, v25, v29
	v_cvt_pk_bf16_f32 v247, v33, v37
	global_store_dwordx4 v206, v[244:247], s[22:23]
	v_cvt_pk_bf16_f32 v248, v41, v45
	v_cvt_pk_bf16_f32 v249, v49, v53
	v_cvt_pk_bf16_f32 v250, v57, v61
	v_cvt_pk_bf16_f32 v251, v65, v69
	global_store_dwordx4 v206, v[248:251], s[22:23] offset:16
	s_add_u32 s22, s22, s4
	s_addc_u32 s23, s23, 0
	v_cvt_pk_bf16_f32 v236, v10, v14
	v_cvt_pk_bf16_f32 v237, v18, v22
	v_cvt_pk_bf16_f32 v238, v26, v30
	v_cvt_pk_bf16_f32 v239, v34, v38
	global_store_dwordx4 v206, v[236:239], s[22:23]
	v_cvt_pk_bf16_f32 v240, v42, v46
	v_cvt_pk_bf16_f32 v241, v50, v54
	v_cvt_pk_bf16_f32 v242, v58, v62
	v_cvt_pk_bf16_f32 v243, v66, v70
	global_store_dwordx4 v206, v[240:243], s[22:23] offset:16
	s_add_u32 s22, s22, s4
	s_addc_u32 s23, s23, 0
	v_cvt_pk_bf16_f32 v244, v11, v15
	v_cvt_pk_bf16_f32 v245, v19, v23
	v_cvt_pk_bf16_f32 v246, v27, v31
	v_cvt_pk_bf16_f32 v247, v35, v39
	global_store_dwordx4 v206, v[244:247], s[22:23]
	v_cvt_pk_bf16_f32 v248, v43, v47
	v_cvt_pk_bf16_f32 v249, v51, v55
	v_cvt_pk_bf16_f32 v250, v59, v63
	v_cvt_pk_bf16_f32 v251, v67, v71
	global_store_dwordx4 v206, v[248:251], s[22:23] offset:16
	s_bitcmp1_b32 s35, 0
	s_cbranch_scc0 .Lw1_nog_5
	s_load_dwordx16 s[80:95], s[32:33], 0x0
	s_load_dwordx16 s[48:63], s[32:33], 0x40
.Lw1_nog_5:
	s_bitcmp1_b32 s35, 1
	s_cselect_b64 vcc, -1, 0
	s_lshr_b32 s0, s35, 8
	s_lshl_b32 s4, 1, s0
	v_cndmask_b32_e32 v207, v202, v203, vcc
	v_lshlrev_b32_e32 v206, s0, v207
	v_add_u32_e32 v206, v206, v204
	s_waitcnt vmcnt(24)
	s_bitcmp1_b32 s35, 0
	s_cbranch_scc0 .Lw1_nomul_5
	s_waitcnt lgkmcnt(0)
	s_mov_b32 exec_hi, 0
	v_mul_f32_e32 v72, s80, v72
	v_mul_f32_e32 v73, s80, v73
	v_mul_f32_e32 v74, s80, v74
	v_mul_f32_e32 v75, s80, v75
	v_mul_f32_e32 v76, s81, v76
	v_mul_f32_e32 v77, s81, v77
	v_mul_f32_e32 v78, s81, v78
	v_mul_f32_e32 v79, s81, v79
	v_mul_f32_e32 v80, s82, v80
	v_mul_f32_e32 v81, s82, v81
	v_mul_f32_e32 v82, s82, v82
	v_mul_f32_e32 v83, s82, v83
	v_mul_f32_e32 v84, s83, v84
	v_mul_f32_e32 v85, s83, v85
	v_mul_f32_e32 v86, s83, v86
	v_mul_f32_e32 v87, s83, v87
	v_mul_f32_e32 v88, s84, v88
	v_mul_f32_e32 v89, s84, v89
	v_mul_f32_e32 v90, s84, v90
	v_mul_f32_e32 v91, s84, v91
	v_mul_f32_e32 v92, s85, v92
	v_mul_f32_e32 v93, s85, v93
	v_mul_f32_e32 v94, s85, v94
	v_mul_f32_e32 v95, s85, v95
	v_mul_f32_e32 v96, s86, v96
	v_mul_f32_e32 v97, s86, v97
	v_mul_f32_e32 v98, s86, v98
	v_mul_f32_e32 v99, s86, v99
	v_mul_f32_e32 v100, s87, v100
	v_mul_f32_e32 v101, s87, v101
	v_mul_f32_e32 v102, s87, v102
	v_mul_f32_e32 v103, s87, v103
	v_mul_f32_e32 v104, s88, v104
	v_mul_f32_e32 v105, s88, v105
	v_mul_f32_e32 v106, s88, v106
	v_mul_f32_e32 v107, s88, v107
	v_mul_f32_e32 v108, s89, v108
	v_mul_f32_e32 v109, s89, v109
	v_mul_f32_e32 v110, s89, v110
	v_mul_f32_e32 v111, s89, v111
	v_mul_f32_e32 v112, s90, v112
	v_mul_f32_e32 v113, s90, v113
	v_mul_f32_e32 v114, s90, v114
	v_mul_f32_e32 v115, s90, v115
	v_mul_f32_e32 v116, s91, v116
	v_mul_f32_e32 v117, s91, v117
	v_mul_f32_e32 v118, s91, v118
	v_mul_f32_e32 v119, s91, v119
	v_mul_f32_e32 v120, s92, v120
	v_mul_f32_e32 v121, s92, v121
	v_mul_f32_e32 v122, s92, v122
	v_mul_f32_e32 v123, s92, v123
	v_mul_f32_e32 v124, s93, v124
	v_mul_f32_e32 v125, s93, v125
	v_mul_f32_e32 v126, s93, v126
	v_mul_f32_e32 v127, s93, v127
	v_mul_f32_e32 v128, s94, v128
	v_mul_f32_e32 v129, s94, v129
	v_mul_f32_e32 v130, s94, v130
	v_mul_f32_e32 v131, s94, v131
	v_mul_f32_e32 v132, s95, v132
	v_mul_f32_e32 v133, s95, v133
	v_mul_f32_e32 v134, s95, v134
	v_mul_f32_e32 v135, s95, v135
	s_mov_b32 exec_lo, 0
	s_mov_b32 exec_hi, -1
	v_mul_f32_e32 v72, s48, v72
	v_mul_f32_e32 v73, s48, v73
	v_mul_f32_e32 v74, s48, v74
	v_mul_f32_e32 v75, s48, v75
	v_mul_f32_e32 v76, s49, v76
	v_mul_f32_e32 v77, s49, v77
	v_mul_f32_e32 v78, s49, v78
	v_mul_f32_e32 v79, s49, v79
	v_mul_f32_e32 v80, s50, v80
	v_mul_f32_e32 v81, s50, v81
	v_mul_f32_e32 v82, s50, v82
	v_mul_f32_e32 v83, s50, v83
	v_mul_f32_e32 v84, s51, v84
	v_mul_f32_e32 v85, s51, v85
	v_mul_f32_e32 v86, s51, v86
	v_mul_f32_e32 v87, s51, v87
	v_mul_f32_e32 v88, s52, v88
	v_mul_f32_e32 v89, s52, v89
	v_mul_f32_e32 v90, s52, v90
	v_mul_f32_e32 v91, s52, v91
	v_mul_f32_e32 v92, s53, v92
	v_mul_f32_e32 v93, s53, v93
	v_mul_f32_e32 v94, s53, v94
	v_mul_f32_e32 v95, s53, v95
	v_mul_f32_e32 v96, s54, v96
	v_mul_f32_e32 v97, s54, v97
	v_mul_f32_e32 v98, s54, v98
	v_mul_f32_e32 v99, s54, v99
	v_mul_f32_e32 v100, s55, v100
	v_mul_f32_e32 v101, s55, v101
	v_mul_f32_e32 v102, s55, v102
	v_mul_f32_e32 v103, s55, v103
	v_mul_f32_e32 v104, s56, v104
	v_mul_f32_e32 v105, s56, v105
	v_mul_f32_e32 v106, s56, v106
	v_mul_f32_e32 v107, s56, v107
	v_mul_f32_e32 v108, s57, v108
	v_mul_f32_e32 v109, s57, v109
	v_mul_f32_e32 v110, s57, v110
	v_mul_f32_e32 v111, s57, v111
	v_mul_f32_e32 v112, s58, v112
	v_mul_f32_e32 v113, s58, v113
	v_mul_f32_e32 v114, s58, v114
	v_mul_f32_e32 v115, s58, v115
	v_mul_f32_e32 v116, s59, v116
	v_mul_f32_e32 v117, s59, v117
	v_mul_f32_e32 v118, s59, v118
	v_mul_f32_e32 v119, s59, v119
	v_mul_f32_e32 v120, s60, v120
	v_mul_f32_e32 v121, s60, v121
	v_mul_f32_e32 v122, s60, v122
	v_mul_f32_e32 v123, s60, v123
	v_mul_f32_e32 v124, s61, v124
	v_mul_f32_e32 v125, s61, v125
	v_mul_f32_e32 v126, s61, v126
	v_mul_f32_e32 v127, s61, v127
	v_mul_f32_e32 v128, s62, v128
	v_mul_f32_e32 v129, s62, v129
	v_mul_f32_e32 v130, s62, v130
	v_mul_f32_e32 v131, s62, v131
	v_mul_f32_e32 v132, s63, v132
	v_mul_f32_e32 v133, s63, v133
	v_mul_f32_e32 v134, s63, v134
	v_mul_f32_e32 v135, s63, v135
	s_mov_b64 exec, -1
.Lw1_nomul_5:
	v_cvt_pk_bf16_f32 v236, v72, v76
	v_cvt_pk_bf16_f32 v237, v80, v84
	v_cvt_pk_bf16_f32 v238, v88, v92
	v_cvt_pk_bf16_f32 v239, v96, v100
	global_store_dwordx4 v206, v[236:239], s[30:31]
	v_cvt_pk_bf16_f32 v240, v104, v108
	v_cvt_pk_bf16_f32 v241, v112, v116
	v_cvt_pk_bf16_f32 v242, v120, v124
	v_cvt_pk_bf16_f32 v243, v128, v132
	global_store_dwordx4 v206, v[240:243], s[30:31] offset:16
	s_add_u32 s30, s30, s4
	s_addc_u32 s31, s31, 0
	v_cvt_pk_bf16_f32 v244, v73, v77
	v_cvt_pk_bf16_f32 v245, v81, v85
	v_cvt_pk_bf16_f32 v246, v89, v93
	v_cvt_pk_bf16_f32 v247, v97, v101
	global_store_dwordx4 v206, v[244:247], s[30:31]
	v_cvt_pk_bf16_f32 v248, v105, v109
	v_cvt_pk_bf16_f32 v249, v113, v117
	v_cvt_pk_bf16_f32 v250, v121, v125
	v_cvt_pk_bf16_f32 v251, v129, v133
	global_store_dwordx4 v206, v[248:251], s[30:31] offset:16
	s_add_u32 s30, s30, s4
	s_addc_u32 s31, s31, 0
	v_cvt_pk_bf16_f32 v236, v74, v78
	v_cvt_pk_bf16_f32 v237, v82, v86
	v_cvt_pk_bf16_f32 v238, v90, v94
	v_cvt_pk_bf16_f32 v239, v98, v102
	global_store_dwordx4 v206, v[236:239], s[30:31]
	v_cvt_pk_bf16_f32 v240, v106, v110
	v_cvt_pk_bf16_f32 v241, v114, v118
	v_cvt_pk_bf16_f32 v242, v122, v126
	v_cvt_pk_bf16_f32 v243, v130, v134
	global_store_dwordx4 v206, v[240:243], s[30:31] offset:16
	s_add_u32 s30, s30, s4
	s_addc_u32 s31, s31, 0
	v_cvt_pk_bf16_f32 v244, v75, v79
	v_cvt_pk_bf16_f32 v245, v83, v87
	v_cvt_pk_bf16_f32 v246, v91, v95
	v_cvt_pk_bf16_f32 v247, v99, v103
	global_store_dwordx4 v206, v[244:247], s[30:31]
	v_cvt_pk_bf16_f32 v248, v107, v111
	v_cvt_pk_bf16_f32 v249, v115, v119
	v_cvt_pk_bf16_f32 v250, v123, v127
	v_cvt_pk_bf16_f32 v251, v131, v135
	global_store_dwordx4 v206, v[248:251], s[30:31] offset:16
	s_bitcmp1_b32 s47, 0
	s_cbranch_scc0 .Lw1_nog_6
	s_load_dwordx16 s[80:95], s[44:45], 0x0
	s_load_dwordx16 s[48:63], s[44:45], 0x40
.Lw1_nog_6:
	s_bitcmp1_b32 s47, 1
	s_cselect_b64 vcc, -1, 0
	s_lshr_b32 s0, s47, 8
	s_lshl_b32 s4, 1, s0
	v_cndmask_b32_e32 v207, v202, v203, vcc
	v_lshlrev_b32_e32 v206, s0, v207
	v_add_u32_e32 v206, v206, v204
	s_waitcnt vmcnt(16)
	s_bitcmp1_b32 s47, 0
	s_cbranch_scc0 .Lw1_nomul_6
	s_waitcnt lgkmcnt(0)
	s_mov_b32 exec_hi, 0
	v_mul_f32_e32 v136, s80, v136
	v_mul_f32_e32 v137, s80, v137
	v_mul_f32_e32 v138, s80, v138
	v_mul_f32_e32 v139, s80, v139
	v_mul_f32_e32 v140, s81, v140
	v_mul_f32_e32 v141, s81, v141
	v_mul_f32_e32 v142, s81, v142
	v_mul_f32_e32 v143, s81, v143
	v_mul_f32_e32 v144, s82, v144
	v_mul_f32_e32 v145, s82, v145
	v_mul_f32_e32 v146, s82, v146
	v_mul_f32_e32 v147, s82, v147
	v_mul_f32_e32 v148, s83, v148
	v_mul_f32_e32 v149, s83, v149
	v_mul_f32_e32 v150, s83, v150
	v_mul_f32_e32 v151, s83, v151
	v_mul_f32_e32 v152, s84, v152
	v_mul_f32_e32 v153, s84, v153
	v_mul_f32_e32 v154, s84, v154
	v_mul_f32_e32 v155, s84, v155
	v_mul_f32_e32 v156, s85, v156
	v_mul_f32_e32 v157, s85, v157
	v_mul_f32_e32 v158, s85, v158
	v_mul_f32_e32 v159, s85, v159
	v_mul_f32_e32 v160, s86, v160
	v_mul_f32_e32 v161, s86, v161
	v_mul_f32_e32 v162, s86, v162
	v_mul_f32_e32 v163, s86, v163
	v_mul_f32_e32 v164, s87, v164
	v_mul_f32_e32 v165, s87, v165
	v_mul_f32_e32 v166, s87, v166
	v_mul_f32_e32 v167, s87, v167
	v_mul_f32_e32 v168, s88, v168
	v_mul_f32_e32 v169, s88, v169
	v_mul_f32_e32 v170, s88, v170
	v_mul_f32_e32 v171, s88, v171
	v_mul_f32_e32 v172, s89, v172
	v_mul_f32_e32 v173, s89, v173
	v_mul_f32_e32 v174, s89, v174
	v_mul_f32_e32 v175, s89, v175
	v_mul_f32_e32 v176, s90, v176
	v_mul_f32_e32 v177, s90, v177
	v_mul_f32_e32 v178, s90, v178
	v_mul_f32_e32 v179, s90, v179
	v_mul_f32_e32 v180, s91, v180
	v_mul_f32_e32 v181, s91, v181
	v_mul_f32_e32 v182, s91, v182
	v_mul_f32_e32 v183, s91, v183
	v_mul_f32_e32 v184, s92, v184
	v_mul_f32_e32 v185, s92, v185
	v_mul_f32_e32 v186, s92, v186
	v_mul_f32_e32 v187, s92, v187
	v_mul_f32_e32 v188, s93, v188
	v_mul_f32_e32 v189, s93, v189
	v_mul_f32_e32 v190, s93, v190
	v_mul_f32_e32 v191, s93, v191
	v_mul_f32_e32 v192, s94, v192
	v_mul_f32_e32 v193, s94, v193
	v_mul_f32_e32 v194, s94, v194
	v_mul_f32_e32 v195, s94, v195
	v_mul_f32_e32 v196, s95, v196
	v_mul_f32_e32 v197, s95, v197
	v_mul_f32_e32 v198, s95, v198
	v_mul_f32_e32 v199, s95, v199
	s_mov_b32 exec_lo, 0
	s_mov_b32 exec_hi, -1
	v_mul_f32_e32 v136, s48, v136
	v_mul_f32_e32 v137, s48, v137
	v_mul_f32_e32 v138, s48, v138
	v_mul_f32_e32 v139, s48, v139
	v_mul_f32_e32 v140, s49, v140
	v_mul_f32_e32 v141, s49, v141
	v_mul_f32_e32 v142, s49, v142
	v_mul_f32_e32 v143, s49, v143
	v_mul_f32_e32 v144, s50, v144
	v_mul_f32_e32 v145, s50, v145
	v_mul_f32_e32 v146, s50, v146
	v_mul_f32_e32 v147, s50, v147
	v_mul_f32_e32 v148, s51, v148
	v_mul_f32_e32 v149, s51, v149
	v_mul_f32_e32 v150, s51, v150
	v_mul_f32_e32 v151, s51, v151
	v_mul_f32_e32 v152, s52, v152
	v_mul_f32_e32 v153, s52, v153
	v_mul_f32_e32 v154, s52, v154
	v_mul_f32_e32 v155, s52, v155
	v_mul_f32_e32 v156, s53, v156
	v_mul_f32_e32 v157, s53, v157
	v_mul_f32_e32 v158, s53, v158
	v_mul_f32_e32 v159, s53, v159
	v_mul_f32_e32 v160, s54, v160
	v_mul_f32_e32 v161, s54, v161
	v_mul_f32_e32 v162, s54, v162
	v_mul_f32_e32 v163, s54, v163
	v_mul_f32_e32 v164, s55, v164
	v_mul_f32_e32 v165, s55, v165
	v_mul_f32_e32 v166, s55, v166
	v_mul_f32_e32 v167, s55, v167
	v_mul_f32_e32 v168, s56, v168
	v_mul_f32_e32 v169, s56, v169
	v_mul_f32_e32 v170, s56, v170
	v_mul_f32_e32 v171, s56, v171
	v_mul_f32_e32 v172, s57, v172
	v_mul_f32_e32 v173, s57, v173
	v_mul_f32_e32 v174, s57, v174
	v_mul_f32_e32 v175, s57, v175
	v_mul_f32_e32 v176, s58, v176
	v_mul_f32_e32 v177, s58, v177
	v_mul_f32_e32 v178, s58, v178
	v_mul_f32_e32 v179, s58, v179
	v_mul_f32_e32 v180, s59, v180
	v_mul_f32_e32 v181, s59, v181
	v_mul_f32_e32 v182, s59, v182
	v_mul_f32_e32 v183, s59, v183
	v_mul_f32_e32 v184, s60, v184
	v_mul_f32_e32 v185, s60, v185
	v_mul_f32_e32 v186, s60, v186
	v_mul_f32_e32 v187, s60, v187
	v_mul_f32_e32 v188, s61, v188
	v_mul_f32_e32 v189, s61, v189
	v_mul_f32_e32 v190, s61, v190
	v_mul_f32_e32 v191, s61, v191
	v_mul_f32_e32 v192, s62, v192
	v_mul_f32_e32 v193, s62, v193
	v_mul_f32_e32 v194, s62, v194
	v_mul_f32_e32 v195, s62, v195
	v_mul_f32_e32 v196, s63, v196
	v_mul_f32_e32 v197, s63, v197
	v_mul_f32_e32 v198, s63, v198
	v_mul_f32_e32 v199, s63, v199
	s_mov_b64 exec, -1
.Lw1_nomul_6:
	v_cvt_pk_bf16_f32 v236, v136, v140
	v_cvt_pk_bf16_f32 v237, v144, v148
	v_cvt_pk_bf16_f32 v238, v152, v156
	v_cvt_pk_bf16_f32 v239, v160, v164
	global_store_dwordx4 v206, v[236:239], s[42:43]
	v_cvt_pk_bf16_f32 v240, v168, v172
	v_cvt_pk_bf16_f32 v241, v176, v180
	v_cvt_pk_bf16_f32 v242, v184, v188
	v_cvt_pk_bf16_f32 v243, v192, v196
	global_store_dwordx4 v206, v[240:243], s[42:43] offset:16
	s_add_u32 s42, s42, s4
	s_addc_u32 s43, s43, 0
	v_cvt_pk_bf16_f32 v244, v137, v141
	v_cvt_pk_bf16_f32 v245, v145, v149
	v_cvt_pk_bf16_f32 v246, v153, v157
	v_cvt_pk_bf16_f32 v247, v161, v165
	global_store_dwordx4 v206, v[244:247], s[42:43]
	v_cvt_pk_bf16_f32 v248, v169, v173
	v_cvt_pk_bf16_f32 v249, v177, v181
	v_cvt_pk_bf16_f32 v250, v185, v189
	v_cvt_pk_bf16_f32 v251, v193, v197
	global_store_dwordx4 v206, v[248:251], s[42:43] offset:16
	s_add_u32 s42, s42, s4
	s_addc_u32 s43, s43, 0
	v_cvt_pk_bf16_f32 v236, v138, v142
	v_cvt_pk_bf16_f32 v237, v146, v150
	v_cvt_pk_bf16_f32 v238, v154, v158
	v_cvt_pk_bf16_f32 v239, v162, v166
	global_store_dwordx4 v206, v[236:239], s[42:43]
	v_cvt_pk_bf16_f32 v240, v170, v174
	v_cvt_pk_bf16_f32 v241, v178, v182
	v_cvt_pk_bf16_f32 v242, v186, v190
	v_cvt_pk_bf16_f32 v243, v194, v198
	global_store_dwordx4 v206, v[240:243], s[42:43] offset:16
	s_add_u32 s42, s42, s4
	s_addc_u32 s43, s43, 0
	v_cvt_pk_bf16_f32 v244, v139, v143
	v_cvt_pk_bf16_f32 v245, v147, v151
	v_cvt_pk_bf16_f32 v246, v155, v159
	v_cvt_pk_bf16_f32 v247, v163, v167
	global_store_dwordx4 v206, v[244:247], s[42:43]
	v_cvt_pk_bf16_f32 v248, v171, v175
	v_cvt_pk_bf16_f32 v249, v179, v183
	v_cvt_pk_bf16_f32 v250, v187, v191
	v_cvt_pk_bf16_f32 v251, v195, v199
	global_store_dwordx4 v206, v[248:251], s[42:43] offset:16
	v_readlane_b32 s8, v254, 0
	v_readlane_b32 s9, v254, 1
	v_readlane_b32 s10, v254, 2
	v_readlane_b32 s11, v254, 3
	v_readlane_b32 s12, v254, 4
	v_readlane_b32 s13, v254, 5
	v_readlane_b32 s14, v254, 6
	v_readlane_b32 s15, v254, 7
	v_readlane_b32 s16, v254, 8
	v_readlane_b32 s17, v254, 9
	v_readlane_b32 s18, v254, 10
	v_readlane_b32 s19, v254, 11
	v_readlane_b32 s20, v254, 12
	v_readlane_b32 s21, v254, 13
	v_readlane_b32 s22, v254, 14
	v_readlane_b32 s23, v254, 15
	v_readlane_b32 s24, v254, 16
	v_readlane_b32 s25, v254, 17
	v_readlane_b32 s26, v254, 18
	v_readlane_b32 s27, v254, 19
	v_readlane_b32 s28, v254, 20
	v_readlane_b32 s29, v254, 21
	v_readlane_b32 s30, v254, 22
	v_readlane_b32 s31, v254, 23
	v_readlane_b32 s32, v254, 24
	v_readlane_b32 s33, v254, 25
	v_readlane_b32 s34, v254, 26
	v_readlane_b32 s35, v254, 27
	v_readlane_b32 s40, v254, 28
	v_readlane_b32 s41, v254, 29
	v_readlane_b32 s42, v254, 30
	v_readlane_b32 s43, v254, 31
	v_readlane_b32 s44, v254, 32
	v_readlane_b32 s45, v254, 33
	v_readlane_b32 s46, v254, 34
	v_readlane_b32 s47, v254, 35
	v_readlane_b32 s48, v254, 36
	v_readlane_b32 s49, v254, 37
	v_readlane_b32 s50, v254, 38
	v_readlane_b32 s51, v254, 39
	v_readlane_b32 s52, v254, 40
	v_readlane_b32 s53, v254, 41
	v_readlane_b32 s54, v254, 42
	v_readlane_b32 s55, v254, 43
	v_readlane_b32 s56, v254, 44
	v_readlane_b32 s57, v254, 45
	v_readlane_b32 s58, v254, 46
	v_readlane_b32 s59, v254, 47
	v_readlane_b32 s60, v254, 48
	v_readlane_b32 s61, v254, 49
	v_readlane_b32 s62, v254, 50
	v_readlane_b32 s63, v254, 51
	v_readlane_b32 s66, v254, 52
	v_readlane_b32 s67, v254, 53
	v_readlane_b32 s68, v254, 54
	v_readlane_b32 s69, v254, 55
	v_readlane_b32 s70, v254, 56
	v_readlane_b32 s71, v254, 57
	v_readlane_b32 s72, v254, 58
	v_readlane_b32 s73, v254, 59
	v_readlane_b32 s74, v254, 60
	v_readlane_b32 s75, v254, 61
	v_readlane_b32 s76, v254, 62
	v_readlane_b32 s77, v254, 63
	v_readlane_b32 s80, v255, 0
	v_readlane_b32 s81, v255, 1
	v_readlane_b32 s82, v255, 2
	v_readlane_b32 s83, v255, 3
	v_readlane_b32 s84, v255, 4
	v_readlane_b32 s85, v255, 5
	v_readlane_b32 s86, v255, 6
	v_readlane_b32 s87, v255, 7
	v_readlane_b32 s88, v255, 8
	v_readlane_b32 s89, v255, 9
	v_readlane_b32 s90, v255, 10
	v_readlane_b32 s91, v255, 11
	v_readlane_b32 s92, v255, 12
	v_readlane_b32 s93, v255, 13
	v_readlane_b32 s94, v255, 14
	v_readlane_b32 s95, v255, 15
.Lw1_skip:
	s_mov_b32 s1, s64
	s_mov_b32 s6, s65
	s_mov_b64 s[4:5], s[52:53]
	s_mov_b64 s[10:11], s[54:55]
	s_mov_b64 s[28:29], s[56:57]
	s_mov_b64 s[30:31], s[58:59]
	s_mov_b64 s[16:17], s[66:67]
	v_readlane_b32 s52, v253, 26
	s_mul_i32 s0, s36, 0xf800
	v_readlane_b32 s53, v253, 27
	v_readlane_b32 s64, v253, 38
	v_readlane_b32 s65, v253, 39
	s_mov_b64 s[52:53], s[4:5]
	s_add_u32 s4, s64, s0
	v_readlane_b32 s66, v253, 40
	s_addc_u32 s5, s65, 0
	v_readlane_b32 s67, v253, 41
	s_mov_b32 s65, s6
	s_add_u32 s6, s66, s82
	v_readlane_b32 s54, v253, 28
	v_readlane_b32 s55, v253, 29
	s_addc_u32 s7, s67, s83
	s_mov_b64 s[66:67], s[16:17]
	v_readlane_b32 s12, v253, 10
	s_mov_b64 s[54:55], s[10:11]
	v_readlane_b32 s13, v253, 11
	s_add_u32 s10, s12, s82
	v_readlane_b32 s14, v253, 12
	s_addc_u32 s11, s13, s83
	v_readlane_b32 s15, v253, 13
	s_add_u32 s12, s14, s82
	s_mul_i32 s92, s36, 0x1e0000
	v_readlane_b32 s56, v253, 30
	s_mov_b32 s64, s1
	s_addc_u32 s13, s15, s83
	s_lshl_b64 s[0:1], s[92:93], 2
	v_readlane_b32 s57, v253, 31
	v_readlane_b32 s16, v253, 14
	v_readlane_b32 s17, v253, 15
	s_add_u32 s14, s56, s0
	s_addc_u32 s15, s57, s1
	s_mul_i32 s16, s36, 0x78000
	v_readlane_b32 s17, v253, 56
	v_readlane_b32 s18, v253, 16
	s_add_u32 s16, s17, s16
	v_readlane_b32 s17, v253, 57
	s_addc_u32 s17, s17, 0
	v_readlane_b32 s18, v253, 58
	v_readlane_b32 s19, v253, 17
	s_add_u32 s18, s18, s0
	v_readlane_b32 s0, v253, 59
	v_readlane_b32 s58, v253, 32
	v_readlane_b32 s24, v253, 22
	s_addc_u32 s19, s0, s1
	s_lshl_b64 s[0:1], s[36:37], 25
	v_readlane_b32 s59, v253, 33
	v_readlane_b32 s20, v253, 18
	v_readlane_b32 s25, v253, 23
	s_add_u32 s24, s58, s0
	v_readlane_b32 s26, v253, 24
	s_addc_u32 s25, s59, s1
	v_readlane_b32 s20, v253, 60
	v_readlane_b32 s61, v253, 35
	v_readlane_b32 s27, v253, 25
	s_add_u32 s26, s20, s0
	v_readlane_b32 s0, v253, 61
	s_mov_b32 s61, 0x70000
	s_mov_b64 s[56:57], s[28:29]
	s_mov_b64 s[58:59], s[30:31]
	s_addc_u32 s27, s0, s1
	v_readlane_b32 s28, v252, 41
	v_readlane_b32 s29, v252, 39
	s_mov_b32 s30, s2
	v_readlane_b32 s60, v253, 34
	v_readlane_b32 s62, v253, 36
	v_readlane_b32 s63, v253, 37
	v_readlane_b32 s21, v253, 19
	v_readlane_b32 s22, v253, 20
	v_readlane_b32 s23, v253, 21
	s_branch .LBB0_444

	.amdhsa_kernel _Z8mega_fwd4Args
		.amdhsa_group_segment_fixed_size 0
		.amdhsa_private_segment_fixed_size 0
		.amdhsa_kernarg_size 400
		.amdhsa_user_sgpr_count 2
		.amdhsa_user_sgpr_dispatch_ptr 0
		.amdhsa_user_sgpr_queue_ptr 0
		.amdhsa_user_sgpr_kernarg_segment_ptr 1
		.amdhsa_user_sgpr_dispatch_id 0
		.amdhsa_user_sgpr_kernarg_preload_length 0
		.amdhsa_user_sgpr_kernarg_preload_offset 0
		.amdhsa_user_sgpr_private_segment_size 0
		.amdhsa_uses_dynamic_stack 0
		.amdhsa_enable_private_segment 0
		.amdhsa_system_sgpr_workgroup_id_x 1
		.amdhsa_system_sgpr_workgroup_id_y 0
		.amdhsa_system_sgpr_workgroup_id_z 0
		.amdhsa_system_sgpr_workgroup_info 0
		.amdhsa_system_vgpr_workitem_id 2
		.amdhsa_next_free_vgpr 256
		.amdhsa_next_free_sgpr 102
		.amdhsa_accum_offset 256
		.amdhsa_reserve_vcc 1
		.amdhsa_float_round_mode_32 0
		.amdhsa_float_round_mode_16_64 0
		.amdhsa_float_denorm_mode_32 3
		.amdhsa_float_denorm_mode_16_64 3
		.amdhsa_dx10_clamp 1
		.amdhsa_ieee_mode 1
		.amdhsa_fp16_overflow 0
		.amdhsa_tg_split 0
		.amdhsa_exception_fp_ieee_invalid_op 0
		.amdhsa_exception_fp_denorm_src 0
		.amdhsa_exception_fp_ieee_div_zero 0
		.amdhsa_exception_fp_ieee_overflow 0
		.amdhsa_exception_fp_ieee_underflow 0
		.amdhsa_exception_fp_ieee_inexact 0
		.amdhsa_exception_int_div_zero 0
	.end_amdhsa_kernel

amdhsa.kernels:
  - .agpr_count:     0
    .args:
      - .offset:         0
        .size:           144
        .value_kind:     by_value
      - .offset:         144
        .size:           4
        .value_kind:     hidden_block_count_x
      - .offset:         148
        .size:           4
        .value_kind:     hidden_block_count_y
      - .offset:         152
        .size:           4
        .value_kind:     hidden_block_count_z
      - .offset:         156
        .size:           2
        .value_kind:     hidden_group_size_x
      - .offset:         158
        .size:           2
        .value_kind:     hidden_group_size_y
      - .offset:         160
        .size:           2
        .value_kind:     hidden_group_size_z
      - .offset:         162
        .size:           2
        .value_kind:     hidden_remainder_x
      - .offset:         164
        .size:           2
        .value_kind:     hidden_remainder_y
      - .offset:         166
        .size:           2
        .value_kind:     hidden_remainder_z
      - .offset:         184
        .size:           8
        .value_kind:     hidden_global_offset_x
      - .offset:         192
        .size:           8
        .value_kind:     hidden_global_offset_y
      - .offset:         200
        .size:           8
        .value_kind:     hidden_global_offset_z
      - .offset:         208
        .size:           2
        .value_kind:     hidden_grid_dims
      - .offset:         232
        .size:           8
        .value_kind:     hidden_multigrid_sync_arg
      - .offset:         264
        .size:           4
        .value_kind:     hidden_dynamic_lds_size
    .group_segment_fixed_size: 0
    .kernarg_segment_align: 8
    .kernarg_segment_size: 400
    .language:       OpenCL C
    .language_version:
      - 2
      - 0
    .max_flat_workgroup_size: 512
    .name:           _Z8mega_fwd4Args
    .private_segment_fixed_size: 0
    .sgpr_count:     108
    .sgpr_spill_count: 116
    .symbol:         _Z8mega_fwd4Args.kd
    .uniform_work_group_size: 1
    .uses_dynamic_stack: false
    .vgpr_count:     256
    .vgpr_spill_count: 0
    .wavefront_size: 64
